# prio3 scheme plus merged vmcnt/lgkmcnt waits at the end of each load segment
# speedup vs baseline: 1.0065x; 1.0065x over previous
; #define PG8_STAGE(bufoff, gbase, voff) do { _Pragma("unroll") for (int _i = 0; _i < 2; ++_i) \
;         __builtin_amdgcn_global_load_lds((const unsigned*)((const char*)(gbase) + (voff)[_i]), (PG8_LAS unsigned*)(lds + (bufoff) + ldsw + _i * 8192), 16, 0, 0); } while (0)
; #define PG8_LDA(dst, b, h) do { _Pragma("unroll") for (int m = 0; m < 4; ++m) _Pragma("unroll") for (int k = 0; k < 2; ++k) dst[m][k] = *(const PG8_LAS bf16x8*)(lds + PG8_SA(b, h) + aoff + m * 2048 + k * 1024); } while (0)
; #define PG8_LDB(dst, b, h) do { _Pragma("unroll") for (int n = 0; n < 2; ++n) _Pragma("unroll") for (int k = 0; k < 2; ++k) dst[n][k] = *(const PG8_LAS bf16x8*)(lds + PG8_SB(b, h) + boff + n * 2048 + k * 1024); } while (0)
; #define PG8_MMA(ai, bj, At, Bt) do { __builtin_amdgcn_s_setprio(1); _Pragma("unroll") for (int m = 0; m < 4; ++m) _Pragma("unroll") for (int n = 0; n < 2; ++n) _Pragma("unroll") for (int k = 0; k < 2; ++k) \
;         acc[ai][bj][m][n] = __builtin_amdgcn_mfma_f32_16x16x32_bf16(Bt[n][k], At[m][k], acc[ai][bj][m][n], 0, 0, 0); __builtin_amdgcn_s_setprio(0); } while (0)
; #define PG8_WAIT_V(n) asm volatile("s_waitcnt vmcnt(" #n ")" ::: "memory")
; #define PG8_WAIT_L(n) asm volatile("s_waitcnt lgkmcnt(" #n ")" ::: "memory")
; template <class Epi, class Sched, bool ALIGN_EPI = false, bool SP2 = false>
; __device__ __forceinline__ void gemm_phase(PG8_LAS unsigned char* lds, const Gemm g, const Sched& S, const Epi& E) {
;     ...
;             const bool last = (t == nt - 2);
;             const char* a1 = cA + (size_t)(t + 1) * kstep;
;             const char* a2 = last ? nA : cA + (size_t)(t + 2) * kstep; const char* b2 = last ? nB : cB + (size_t)(t + 2) * kstep;
;             const char* a3 = a2 + kstep; const char* b3 = b2 + kstep;
;             if (last && has_next) S.a_ready(nxt);
;             if constexpr (SP2) {
;             PG8_LDB(B0, 0, 0); PG8_LDB(B1, 0, 1); PG8_SCHED; PG8_LDA(At, 0, 0); PG8_STAGE(PG8_SA(1, 1), a1 + hstep, voffA);
;             PG8_WAIT_V(8); PG8_WAIT_L(0); PG8_BAR; PG8_MMA(0, 0, At, B0); PG8_MMA(0, 1, At, B1); PG8_BAR; PG8_SCHED;
;             PG8_LDA(At, 0, 1); PG8_STAGE(PG8_SB(0, 0), b2, voffB); PG8_STAGE(PG8_SB(0, 1), b2 + hstep, voffB); PG8_STAGE(PG8_SA(0, 0), a2, voffA);
;             PG8_WAIT_V(8); PG8_WAIT_L(0); PG8_BAR; PG8_MMA(1, 0, At, B0); PG8_MMA(1, 1, At, B1); PG8_BAR; PG8_SCHED;
.LBB0_301:
	s_add_u32 s38, s36, 0xfff80080
	s_addc_u32 s39, s37, -1
	s_add_i32 s61, 0, 0x10000
	s_cmp_eq_u32 s60, 28
	s_cselect_b32 s41, s11, s39
	s_cselect_b32 s40, s13, s38
	s_cselect_b32 s39, s56, s59
	s_cselect_b32 s38, s57, s58
	s_add_i32 s64, 0, 0x14000
	v_add_u32_e32 v158, s61, v150
	v_add_u32_e32 v162, s64, v150
	ds_read_b128 v[142:145], v158
	ds_read_b128 v[146:149], v158 offset:1024
	ds_read_b128 v[154:157], v158 offset:2048
	ds_read_b128 v[158:161], v158 offset:3072
	ds_read_b128 v[174:177], v162
	ds_read_b128 v[178:181], v162 offset:1024
	ds_read_b128 v[204:207], v162 offset:2048
	ds_read_b128 v[208:211], v162 offset:3072
	s_add_i32 m0, s47, 0xc000
	ds_read_b128 v[212:215], v153
	ds_read_b128 v[216:219], v153 offset:1024
	ds_read_b128 v[220:223], v153 offset:2048
	ds_read_b128 v[224:227], v153 offset:3072
	ds_read_b128 v[228:231], v153 offset:4096
	ds_read_b128 v[232:235], v153 offset:5120
	ds_read_b128 v[236:239], v153 offset:6144
	ds_read_b128 v[240:243], v153 offset:7168
	global_load_lds_dwordx4 v138, s[36:37]
	s_add_i32 m0, s47, 0xe000
	s_nop 0
	global_load_lds_dwordx4 v140, s[36:37]
	s_nop 0
	s_waitcnt vmcnt(8) lgkmcnt(0)
	s_barrier
	s_setprio 0
	s_waitcnt lgkmcnt(0)
	v_mfma_f32_16x16x32_bf16 v[128:131], v[142:145], v[212:215], v[128:131]
	v_mfma_f32_16x16x32_bf16 v[120:123], v[154:157], v[212:215], v[120:123]
	v_mfma_f32_16x16x32_bf16 v[112:115], v[142:145], v[220:223], v[112:115]
	v_mfma_f32_16x16x32_bf16 v[104:107], v[154:157], v[220:223], v[104:107]
	v_mfma_f32_16x16x32_bf16 v[96:99], v[142:145], v[228:231], v[96:99]
	v_mfma_f32_16x16x32_bf16 v[88:91], v[154:157], v[228:231], v[88:91]
	v_mfma_f32_16x16x32_bf16 v[80:83], v[142:145], v[236:239], v[80:83]
	v_mfma_f32_16x16x32_bf16 v[72:75], v[154:157], v[236:239], v[72:75]
	v_mfma_f32_16x16x32_bf16 v[128:131], v[146:149], v[216:219], v[128:131]
	v_mfma_f32_16x16x32_bf16 v[120:123], v[158:161], v[216:219], v[120:123]
	v_mfma_f32_16x16x32_bf16 v[112:115], v[146:149], v[224:227], v[112:115]
	v_mfma_f32_16x16x32_bf16 v[104:107], v[158:161], v[224:227], v[104:107]
	v_mfma_f32_16x16x32_bf16 v[96:99], v[146:149], v[232:235], v[96:99]
	v_mfma_f32_16x16x32_bf16 v[88:91], v[158:161], v[232:235], v[88:91]
	v_mfma_f32_16x16x32_bf16 v[80:83], v[146:149], v[240:243], v[80:83]
	v_mfma_f32_16x16x32_bf16 v[72:75], v[158:161], v[240:243], v[72:75]
	v_mfma_f32_16x16x32_bf16 v[124:127], v[174:177], v[212:215], v[124:127]
	v_mfma_f32_16x16x32_bf16 v[116:119], v[204:207], v[212:215], v[116:119]
	v_mfma_f32_16x16x32_bf16 v[108:111], v[174:177], v[220:223], v[108:111]
	v_mfma_f32_16x16x32_bf16 v[100:103], v[204:207], v[220:223], v[100:103]
	v_mfma_f32_16x16x32_bf16 v[92:95], v[174:177], v[228:231], v[92:95]
	v_mfma_f32_16x16x32_bf16 v[84:87], v[204:207], v[228:231], v[84:87]
	v_mfma_f32_16x16x32_bf16 v[76:79], v[174:177], v[236:239], v[76:79]
	v_mfma_f32_16x16x32_bf16 v[68:71], v[204:207], v[236:239], v[68:71]
	v_mfma_f32_16x16x32_bf16 v[124:127], v[178:181], v[216:219], v[124:127]
	v_mfma_f32_16x16x32_bf16 v[116:119], v[208:211], v[216:219], v[116:119]
	v_mfma_f32_16x16x32_bf16 v[108:111], v[178:181], v[224:227], v[108:111]
	v_mfma_f32_16x16x32_bf16 v[100:103], v[208:211], v[224:227], v[100:103]
	v_mfma_f32_16x16x32_bf16 v[92:95], v[178:181], v[232:235], v[92:95]
	v_mfma_f32_16x16x32_bf16 v[84:87], v[208:211], v[232:235], v[84:87]
	v_mfma_f32_16x16x32_bf16 v[76:79], v[178:181], v[240:243], v[76:79]
	v_mfma_f32_16x16x32_bf16 v[68:71], v[208:211], v[240:243], v[68:71]
	s_setprio 3
	s_barrier
	s_add_i32 s61, s61, s42
	s_mov_b32 m0, s61
	ds_read_b128 v[212:215], v153 offset:16384
	ds_read_b128 v[216:219], v153 offset:17408
	ds_read_b128 v[220:223], v153 offset:18432
	ds_read_b128 v[224:227], v153 offset:19456
	ds_read_b128 v[228:231], v153 offset:20480
	ds_read_b128 v[232:235], v153 offset:21504
	ds_read_b128 v[236:239], v153 offset:22528
	ds_read_b128 v[240:243], v153 offset:23552
	global_load_lds_dwordx4 v2, s[38:39]
	s_add_i32 m0, s61, 0x2000
	s_add_u32 s62, s38, 0x80000
	s_addc_u32 s63, s39, 0
	s_add_i32 s61, s64, s42
	global_load_lds_dwordx4 v132, s[38:39]
	s_mov_b32 m0, s61
	s_nop 0
	global_load_lds_dwordx4 v2, s[62:63]
	s_add_i32 m0, s61, 0x2000
	s_nop 0
	global_load_lds_dwordx4 v132, s[62:63]
	s_mov_b32 m0, s47
	s_nop 0
	global_load_lds_dwordx4 v136, s[40:41]
	s_mov_b32 m0, s48
	s_nop 0
	global_load_lds_dwordx4 v134, s[40:41]
	s_nop 0
	s_waitcnt vmcnt(8) lgkmcnt(0)
	s_barrier
	s_setprio 0
	s_waitcnt lgkmcnt(0)
	v_mfma_f32_16x16x32_bf16 v[64:67], v[142:145], v[212:215], v[64:67]
	v_mfma_f32_16x16x32_bf16 v[56:59], v[154:157], v[212:215], v[56:59]
	v_mfma_f32_16x16x32_bf16 v[48:51], v[142:145], v[220:223], v[48:51]
	v_mfma_f32_16x16x32_bf16 v[40:43], v[154:157], v[220:223], v[40:43]
	v_mfma_f32_16x16x32_bf16 v[32:35], v[142:145], v[228:231], v[32:35]
	v_mfma_f32_16x16x32_bf16 v[24:27], v[154:157], v[228:231], v[24:27]
	v_mfma_f32_16x16x32_bf16 v[16:19], v[142:145], v[236:239], v[16:19]
	v_mfma_f32_16x16x32_bf16 v[8:11], v[154:157], v[236:239], v[8:11]
	v_mfma_f32_16x16x32_bf16 v[64:67], v[146:149], v[216:219], v[64:67]
	v_mfma_f32_16x16x32_bf16 v[56:59], v[158:161], v[216:219], v[56:59]
	v_mfma_f32_16x16x32_bf16 v[48:51], v[146:149], v[224:227], v[48:51]
	v_mfma_f32_16x16x32_bf16 v[40:43], v[158:161], v[224:227], v[40:43]
	v_mfma_f32_16x16x32_bf16 v[32:35], v[146:149], v[232:235], v[32:35]
	v_mfma_f32_16x16x32_bf16 v[24:27], v[158:161], v[232:235], v[24:27]
	v_mfma_f32_16x16x32_bf16 v[16:19], v[146:149], v[240:243], v[16:19]
	v_mfma_f32_16x16x32_bf16 v[8:11], v[158:161], v[240:243], v[8:11]
	v_mfma_f32_16x16x32_bf16 v[60:63], v[174:177], v[212:215], v[60:63]
	v_mfma_f32_16x16x32_bf16 v[52:55], v[204:207], v[212:215], v[52:55]
	v_mfma_f32_16x16x32_bf16 v[44:47], v[174:177], v[220:223], v[44:47]
	v_mfma_f32_16x16x32_bf16 v[36:39], v[204:207], v[220:223], v[36:39]
	v_mfma_f32_16x16x32_bf16 v[28:31], v[174:177], v[228:231], v[28:31]
	v_mfma_f32_16x16x32_bf16 v[20:23], v[204:207], v[228:231], v[20:23]
	v_mfma_f32_16x16x32_bf16 v[12:15], v[174:177], v[236:239], v[12:15]
	v_mfma_f32_16x16x32_bf16 v[4:7], v[204:207], v[236:239], v[4:7]
	v_mfma_f32_16x16x32_bf16 v[60:63], v[178:181], v[216:219], v[60:63]
	v_mfma_f32_16x16x32_bf16 v[52:55], v[208:211], v[216:219], v[52:55]
	v_mfma_f32_16x16x32_bf16 v[44:47], v[178:181], v[224:227], v[44:47]
	v_mfma_f32_16x16x32_bf16 v[36:39], v[208:211], v[224:227], v[36:39]
	v_mfma_f32_16x16x32_bf16 v[28:31], v[178:181], v[232:235], v[28:31]
	v_mfma_f32_16x16x32_bf16 v[20:23], v[208:211], v[232:235], v[20:23]
	v_mfma_f32_16x16x32_bf16 v[12:15], v[178:181], v[240:243], v[12:15]
	v_mfma_f32_16x16x32_bf16 v[4:7], v[208:211], v[240:243], v[4:7]
	s_setprio 3
	s_barrier
; #define PG8_STAGE(bufoff, gbase, voff) do { _Pragma("unroll") for (int _i = 0; _i < 2; ++_i) \
;         __builtin_amdgcn_global_load_lds((const unsigned*)((const char*)(gbase) + (voff)[_i]), (PG8_LAS unsigned*)(lds + (bufoff) + ldsw + _i * 8192), 16, 0, 0); } while (0)
; #define PG8_LDA(dst, b, h) do { _Pragma("unroll") for (int m = 0; m < 4; ++m) _Pragma("unroll") for (int k = 0; k < 2; ++k) dst[m][k] = *(const PG8_LAS bf16x8*)(lds + PG8_SA(b, h) + aoff + m * 2048 + k * 1024); } while (0)
; #define PG8_LDB(dst, b, h) do { _Pragma("unroll") for (int n = 0; n < 2; ++n) _Pragma("unroll") for (int k = 0; k < 2; ++k) dst[n][k] = *(const PG8_LAS bf16x8*)(lds + PG8_SB(b, h) + boff + n * 2048 + k * 1024); } while (0)
; #define PG8_MMA(ai, bj, At, Bt) do { __builtin_amdgcn_s_setprio(1); _Pragma("unroll") for (int m = 0; m < 4; ++m) _Pragma("unroll") for (int n = 0; n < 2; ++n) _Pragma("unroll") for (int k = 0; k < 2; ++k) \
;         acc[ai][bj][m][n] = __builtin_amdgcn_mfma_f32_16x16x32_bf16(Bt[n][k], At[m][k], acc[ai][bj][m][n], 0, 0, 0); __builtin_amdgcn_s_setprio(0); } while (0)
; #define PG8_WAIT_V(n) asm volatile("s_waitcnt vmcnt(" #n ")" ::: "memory")
; #define PG8_WAIT_L(n) asm volatile("s_waitcnt lgkmcnt(" #n ")" ::: "memory")
; #define PG8_BAR __builtin_amdgcn_s_barrier()
; #define PG8_SCHED __builtin_amdgcn_sched_barrier(0)
; template <class Epi, class Sched, bool ALIGN_EPI = false, bool SP2 = false>
; __device__ __forceinline__ void gemm_phase(PG8_LAS unsigned char* lds, const Gemm g, const Sched& S, const Epi& E) {
;     ...
;             PG8_LDB(B0, 1, 0); PG8_LDB(B1, 1, 1); PG8_SCHED; PG8_LDA(At, 1, 0); PG8_STAGE(PG8_SA(0, 1), a2 + hstep, voffA);
;             PG8_WAIT_V(8); PG8_WAIT_L(0); PG8_BAR; PG8_MMA(0, 0, At, B0); PG8_MMA(0, 1, At, B1); PG8_BAR; PG8_SCHED;
;             PG8_LDA(At, 1, 1); PG8_STAGE(PG8_SB(1, 0), b3, voffB); PG8_STAGE(PG8_SB(1, 1), b3 + hstep, voffB); PG8_STAGE(PG8_SA(1, 0), a3, voffA);
;             PG8_WAIT_V(8); PG8_WAIT_L(0); PG8_BAR; PG8_MMA(1, 0, At, B0); PG8_MMA(1, 1, At, B1); PG8_BAR; PG8_SCHED;
	s_add_i32 s61, 0, 0x18000
	s_add_i32 s62, 0, 0x1c000
	v_add_u32_e32 v158, s61, v150
	v_add_u32_e32 v164, s62, v150
	ds_read_b128 v[142:145], v158
	ds_read_b128 v[146:149], v158 offset:1024
	ds_read_b128 v[154:157], v158 offset:2048
	ds_read_b128 v[158:161], v158 offset:3072
	ds_read_b128 v[174:177], v164
	ds_read_b128 v[178:181], v164 offset:1024
	ds_read_b128 v[204:207], v164 offset:2048
	ds_read_b128 v[208:211], v164 offset:3072
	s_add_u32 s100, s40, 0x80
	s_addc_u32 s101, s41, 0
	s_add_u32 s40, s40, 0x80000
	s_addc_u32 s41, s41, 0
	s_mov_b32 m0, s49
	ds_read_b128 v[212:215], v153 offset:32768
	ds_read_b128 v[216:219], v153 offset:33792
	ds_read_b128 v[220:223], v153 offset:34816
	ds_read_b128 v[224:227], v153 offset:35840
	ds_read_b128 v[228:231], v153 offset:36864
	ds_read_b128 v[232:235], v153 offset:37888
	ds_read_b128 v[236:239], v153 offset:38912
	ds_read_b128 v[240:243], v153 offset:39936
	global_load_lds_dwordx4 v136, s[40:41]
	s_mov_b32 m0, s50
	s_nop 0
	global_load_lds_dwordx4 v134, s[40:41]
	s_nop 0
	s_waitcnt vmcnt(8) lgkmcnt(0)
	s_barrier
	s_setprio 0
	s_waitcnt lgkmcnt(0)
	v_mfma_f32_16x16x32_bf16 v[128:131], v[142:145], v[212:215], v[128:131]
	v_mfma_f32_16x16x32_bf16 v[120:123], v[154:157], v[212:215], v[120:123]
	v_mfma_f32_16x16x32_bf16 v[112:115], v[142:145], v[220:223], v[112:115]
	v_mfma_f32_16x16x32_bf16 v[104:107], v[154:157], v[220:223], v[104:107]
	v_mfma_f32_16x16x32_bf16 v[96:99], v[142:145], v[228:231], v[96:99]
	v_mfma_f32_16x16x32_bf16 v[88:91], v[154:157], v[228:231], v[88:91]
	v_mfma_f32_16x16x32_bf16 v[80:83], v[142:145], v[236:239], v[80:83]
	v_mfma_f32_16x16x32_bf16 v[72:75], v[154:157], v[236:239], v[72:75]
	v_mfma_f32_16x16x32_bf16 v[128:131], v[146:149], v[216:219], v[128:131]
	v_mfma_f32_16x16x32_bf16 v[120:123], v[158:161], v[216:219], v[120:123]
	v_mfma_f32_16x16x32_bf16 v[112:115], v[146:149], v[224:227], v[112:115]
	v_mfma_f32_16x16x32_bf16 v[104:107], v[158:161], v[224:227], v[104:107]
	v_mfma_f32_16x16x32_bf16 v[96:99], v[146:149], v[232:235], v[96:99]
	v_mfma_f32_16x16x32_bf16 v[88:91], v[158:161], v[232:235], v[88:91]
	v_mfma_f32_16x16x32_bf16 v[80:83], v[146:149], v[240:243], v[80:83]
	v_mfma_f32_16x16x32_bf16 v[72:75], v[158:161], v[240:243], v[72:75]
	v_mfma_f32_16x16x32_bf16 v[124:127], v[174:177], v[212:215], v[124:127]
	v_mfma_f32_16x16x32_bf16 v[116:119], v[204:207], v[212:215], v[116:119]
	v_mfma_f32_16x16x32_bf16 v[108:111], v[174:177], v[220:223], v[108:111]
	v_mfma_f32_16x16x32_bf16 v[100:103], v[204:207], v[220:223], v[100:103]
	v_mfma_f32_16x16x32_bf16 v[92:95], v[174:177], v[228:231], v[92:95]
	v_mfma_f32_16x16x32_bf16 v[84:87], v[204:207], v[228:231], v[84:87]
	v_mfma_f32_16x16x32_bf16 v[76:79], v[174:177], v[236:239], v[76:79]
	v_mfma_f32_16x16x32_bf16 v[68:71], v[204:207], v[236:239], v[68:71]
	v_mfma_f32_16x16x32_bf16 v[124:127], v[178:181], v[216:219], v[124:127]
	v_mfma_f32_16x16x32_bf16 v[116:119], v[208:211], v[216:219], v[116:119]
	v_mfma_f32_16x16x32_bf16 v[108:111], v[178:181], v[224:227], v[108:111]
	v_mfma_f32_16x16x32_bf16 v[100:103], v[208:211], v[224:227], v[100:103]
	v_mfma_f32_16x16x32_bf16 v[92:95], v[178:181], v[232:235], v[92:95]
	v_mfma_f32_16x16x32_bf16 v[84:87], v[208:211], v[232:235], v[84:87]
	v_mfma_f32_16x16x32_bf16 v[76:79], v[178:181], v[240:243], v[76:79]
	v_mfma_f32_16x16x32_bf16 v[68:71], v[208:211], v[240:243], v[68:71]
	s_setprio 3
	s_barrier
	s_add_i32 s40, s61, s42
	s_add_i32 m0, s40, 0xffffff80
	ds_read_b128 v[212:215], v153 offset:49152
	ds_read_b128 v[216:219], v153 offset:50176
	ds_read_b128 v[220:223], v153 offset:51200
	ds_read_b128 v[224:227], v153 offset:52224
	ds_read_b128 v[228:231], v153 offset:53248
	ds_read_b128 v[232:235], v153 offset:54272
	ds_read_b128 v[236:239], v153 offset:55296
	ds_read_b128 v[240:243], v153 offset:56320
	global_load_lds_dwordx4 v2, s[38:39] offset:128
	s_add_i32 m0, s40, 0x1f80
	s_add_i32 s40, s62, s42
	global_load_lds_dwordx4 v132, s[38:39] offset:128
	s_add_u32 s38, s38, 0x80080
	s_addc_u32 s39, s39, 0
	s_mov_b32 m0, s40
	s_nop 0
	global_load_lds_dwordx4 v2, s[38:39]
	s_add_i32 m0, s40, 0x2000
	s_nop 0
	global_load_lds_dwordx4 v132, s[38:39]
	s_mov_b32 m0, s51
	s_nop 0
	global_load_lds_dwordx4 v136, s[100:101]
	s_mov_b32 m0, s53
	s_nop 0
	global_load_lds_dwordx4 v134, s[100:101]
	s_waitcnt vmcnt(8) lgkmcnt(0)
	s_barrier
	s_setprio 0
	s_waitcnt lgkmcnt(0)
	v_mfma_f32_16x16x32_bf16 v[64:67], v[142:145], v[212:215], v[64:67]
	v_mfma_f32_16x16x32_bf16 v[56:59], v[154:157], v[212:215], v[56:59]
	v_mfma_f32_16x16x32_bf16 v[48:51], v[142:145], v[220:223], v[48:51]
	v_mfma_f32_16x16x32_bf16 v[40:43], v[154:157], v[220:223], v[40:43]
	v_mfma_f32_16x16x32_bf16 v[32:35], v[142:145], v[228:231], v[32:35]
	v_mfma_f32_16x16x32_bf16 v[24:27], v[154:157], v[228:231], v[24:27]
	v_mfma_f32_16x16x32_bf16 v[16:19], v[142:145], v[236:239], v[16:19]
	v_mfma_f32_16x16x32_bf16 v[8:11], v[154:157], v[236:239], v[8:11]
	v_mfma_f32_16x16x32_bf16 v[64:67], v[146:149], v[216:219], v[64:67]
	v_mfma_f32_16x16x32_bf16 v[56:59], v[158:161], v[216:219], v[56:59]
	v_mfma_f32_16x16x32_bf16 v[48:51], v[146:149], v[224:227], v[48:51]
	v_mfma_f32_16x16x32_bf16 v[40:43], v[158:161], v[224:227], v[40:43]
	v_mfma_f32_16x16x32_bf16 v[32:35], v[146:149], v[232:235], v[32:35]
	v_mfma_f32_16x16x32_bf16 v[24:27], v[158:161], v[232:235], v[24:27]
	v_mfma_f32_16x16x32_bf16 v[16:19], v[146:149], v[240:243], v[16:19]
	v_mfma_f32_16x16x32_bf16 v[8:11], v[158:161], v[240:243], v[8:11]
	v_mfma_f32_16x16x32_bf16 v[60:63], v[174:177], v[212:215], v[60:63]
	v_mfma_f32_16x16x32_bf16 v[52:55], v[204:207], v[212:215], v[52:55]
	v_mfma_f32_16x16x32_bf16 v[44:47], v[174:177], v[220:223], v[44:47]
	v_mfma_f32_16x16x32_bf16 v[36:39], v[204:207], v[220:223], v[36:39]
	v_mfma_f32_16x16x32_bf16 v[28:31], v[174:177], v[228:231], v[28:31]
	v_mfma_f32_16x16x32_bf16 v[20:23], v[204:207], v[228:231], v[20:23]
	v_mfma_f32_16x16x32_bf16 v[12:15], v[174:177], v[236:239], v[12:15]
	v_mfma_f32_16x16x32_bf16 v[4:7], v[204:207], v[236:239], v[4:7]
	v_mfma_f32_16x16x32_bf16 v[60:63], v[178:181], v[216:219], v[60:63]
	v_mfma_f32_16x16x32_bf16 v[52:55], v[208:211], v[216:219], v[52:55]
	v_mfma_f32_16x16x32_bf16 v[44:47], v[178:181], v[224:227], v[44:47]
	v_mfma_f32_16x16x32_bf16 v[36:39], v[208:211], v[224:227], v[36:39]
	v_mfma_f32_16x16x32_bf16 v[28:31], v[178:181], v[232:235], v[28:31]
	v_mfma_f32_16x16x32_bf16 v[20:23], v[208:211], v[232:235], v[20:23]
	v_mfma_f32_16x16x32_bf16 v[12:15], v[178:181], v[240:243], v[12:15]
	v_mfma_f32_16x16x32_bf16 v[4:7], v[208:211], v[240:243], v[4:7]
	s_setprio 3
	s_barrier
	s_add_i32 s60, s60, 2
	s_add_u32 s36, s36, 0x100
	s_addc_u32 s37, s37, 0
	s_add_u32 s58, s58, 0x100
	s_addc_u32 s59, s59, 0
	s_cmp_gt_u32 s60, 29
	s_cbranch_scc0 .LBB0_301
	s_and_b64 vcc, exec, s[8:9]
	s_cbranch_vccz .LBB0_304
	s_barrier

; #define PG8_STAGE(bufoff, gbase, voff) do { _Pragma("unroll") for (int _i = 0; _i < 2; ++_i) \
;         __builtin_amdgcn_global_load_lds((const unsigned*)((const char*)(gbase) + (voff)[_i]), (PG8_LAS unsigned*)(lds + (bufoff) + ldsw + _i * 8192), 16, 0, 0); } while (0)
; #define PG8_LDA(dst, b, h) do { _Pragma("unroll") for (int m = 0; m < 4; ++m) _Pragma("unroll") for (int k = 0; k < 2; ++k) dst[m][k] = *(const PG8_LAS bf16x8*)(lds + PG8_SA(b, h) + aoff + m * 2048 + k * 1024); } while (0)
; #define PG8_LDB(dst, b, h) do { _Pragma("unroll") for (int n = 0; n < 2; ++n) _Pragma("unroll") for (int k = 0; k < 2; ++k) dst[n][k] = *(const PG8_LAS bf16x8*)(lds + PG8_SB(b, h) + boff + n * 2048 + k * 1024); } while (0)
; #define PG8_MMA(ai, bj, At, Bt) do { __builtin_amdgcn_s_setprio(1); _Pragma("unroll") for (int m = 0; m < 4; ++m) _Pragma("unroll") for (int n = 0; n < 2; ++n) _Pragma("unroll") for (int k = 0; k < 2; ++k) \
;         acc[ai][bj][m][n] = __builtin_amdgcn_mfma_f32_16x16x32_bf16(Bt[n][k], At[m][k], acc[ai][bj][m][n], 0, 0, 0); __builtin_amdgcn_s_setprio(0); } while (0)
; #define PG8_WAIT_V(n) asm volatile("s_waitcnt vmcnt(" #n ")" ::: "memory")
; #define PG8_WAIT_L(n) asm volatile("s_waitcnt lgkmcnt(" #n ")" ::: "memory")
; template <class Epi, class Sched, bool ALIGN_EPI = false, bool SP2 = false>
; __device__ __forceinline__ void gemm_phase(PG8_LAS unsigned char* lds, const Gemm g, const Sched& S, const Epi& E) {
;     ...
;             const bool last = (t == nt - 2);
;             const char* a1 = cA + (size_t)(t + 1) * kstep;
;             const char* a2 = last ? nA : cA + (size_t)(t + 2) * kstep; const char* b2 = last ? nB : cB + (size_t)(t + 2) * kstep;
;             const char* a3 = a2 + kstep; const char* b3 = b2 + kstep;
;             if (last && has_next) S.a_ready(nxt);
;             if constexpr (SP2) {
;             PG8_LDB(B0, 0, 0); PG8_LDB(B1, 0, 1); PG8_SCHED; PG8_LDA(At, 0, 0); PG8_STAGE(PG8_SA(1, 1), a1 + hstep, voffA);
;             PG8_WAIT_V(8); PG8_WAIT_L(0); PG8_BAR; PG8_MMA(0, 0, At, B0); PG8_MMA(0, 1, At, B1); PG8_BAR; PG8_SCHED;
;             PG8_LDA(At, 0, 1); PG8_STAGE(PG8_SB(0, 0), b2, voffB); PG8_STAGE(PG8_SB(0, 1), b2 + hstep, voffB); PG8_STAGE(PG8_SA(0, 0), a2, voffA);
;             PG8_WAIT_V(8); PG8_WAIT_L(0); PG8_BAR; PG8_MMA(1, 0, At, B0); PG8_MMA(1, 1, At, B1); PG8_BAR; PG8_SCHED;
.LBB0_575:
	s_add_u32 s36, s34, 0x100
	s_addc_u32 s37, s35, 0
	s_add_i32 s64, 0, 0x10000
	s_cmpk_eq_i32 s63, 0x52
	s_cselect_b32 s41, s5, s37
	s_cselect_b32 s40, s4, s36
	v_add_u32_e32 v135, s64, v173
	s_cselect_b32 s39, s31, s62
	s_cselect_b32 s38, s30, s61
	s_add_i32 s65, 0, 0x14000
	ds_read_b128 v[142:145], v135
	ds_read_b128 v[146:149], v135 offset:1024
	ds_read_b128 v[150:153], v135 offset:2048
	ds_read_b128 v[154:157], v135 offset:3072
	v_add_u32_e32 v135, s65, v173
	ds_read_b128 v[158:161], v135
	ds_read_b128 v[174:177], v135 offset:1024
	ds_read_b128 v[180:183], v135 offset:2048
	ds_read_b128 v[204:207], v135 offset:3072
	v_lshl_add_u64 v[162:163], s[34:35], 0, v[138:139]
	s_add_i32 m0, s47, 0xc000
	ds_read_b128 v[208:211], v179
	ds_read_b128 v[212:215], v179 offset:1024
	ds_read_b128 v[216:219], v179 offset:2048
	ds_read_b128 v[220:223], v179 offset:3072
	ds_read_b128 v[224:227], v179 offset:4096
	ds_read_b128 v[228:231], v179 offset:5120
	ds_read_b128 v[232:235], v179 offset:6144
	ds_read_b128 v[236:239], v179 offset:7168
	global_load_lds_dwordx4 v[162:163], off
	v_lshl_add_u64 v[162:163], s[34:35], 0, v[140:141]
	s_add_i32 m0, s47, 0xe000
	s_nop 0
	global_load_lds_dwordx4 v[162:163], off
	s_nop 0
	s_waitcnt vmcnt(8) lgkmcnt(0)
	s_barrier
	s_setprio 0
	s_waitcnt lgkmcnt(0)
	v_mfma_f32_16x16x32_bf16 v[128:131], v[142:145], v[208:211], v[128:131]
	v_mfma_f32_16x16x32_bf16 v[124:127], v[150:153], v[208:211], v[124:127]
	v_mfma_f32_16x16x32_bf16 v[112:115], v[142:145], v[216:219], v[112:115]
	v_mfma_f32_16x16x32_bf16 v[108:111], v[150:153], v[216:219], v[108:111]
	v_mfma_f32_16x16x32_bf16 v[96:99], v[142:145], v[224:227], v[96:99]
	v_mfma_f32_16x16x32_bf16 v[92:95], v[150:153], v[224:227], v[92:95]
	v_mfma_f32_16x16x32_bf16 v[80:83], v[142:145], v[232:235], v[80:83]
	v_mfma_f32_16x16x32_bf16 v[76:79], v[150:153], v[232:235], v[76:79]
	v_mfma_f32_16x16x32_bf16 v[128:131], v[146:149], v[212:215], v[128:131]
	v_mfma_f32_16x16x32_bf16 v[124:127], v[154:157], v[212:215], v[124:127]
	v_mfma_f32_16x16x32_bf16 v[112:115], v[146:149], v[220:223], v[112:115]
	v_mfma_f32_16x16x32_bf16 v[108:111], v[154:157], v[220:223], v[108:111]
	v_mfma_f32_16x16x32_bf16 v[96:99], v[146:149], v[228:231], v[96:99]
	v_mfma_f32_16x16x32_bf16 v[92:95], v[154:157], v[228:231], v[92:95]
	v_mfma_f32_16x16x32_bf16 v[80:83], v[146:149], v[236:239], v[80:83]
	v_mfma_f32_16x16x32_bf16 v[76:79], v[154:157], v[236:239], v[76:79]
	v_mfma_f32_16x16x32_bf16 v[120:123], v[158:161], v[208:211], v[120:123]
	v_mfma_f32_16x16x32_bf16 v[116:119], v[180:183], v[208:211], v[116:119]
	v_mfma_f32_16x16x32_bf16 v[104:107], v[158:161], v[216:219], v[104:107]
	v_mfma_f32_16x16x32_bf16 v[100:103], v[180:183], v[216:219], v[100:103]
	v_mfma_f32_16x16x32_bf16 v[88:91], v[158:161], v[224:227], v[88:91]
	v_mfma_f32_16x16x32_bf16 v[84:87], v[180:183], v[224:227], v[84:87]
	v_mfma_f32_16x16x32_bf16 v[72:75], v[158:161], v[232:235], v[72:75]
	v_mfma_f32_16x16x32_bf16 v[68:71], v[180:183], v[232:235], v[68:71]
	v_mfma_f32_16x16x32_bf16 v[120:123], v[174:177], v[212:215], v[120:123]
	v_mfma_f32_16x16x32_bf16 v[116:119], v[204:207], v[212:215], v[116:119]
	v_mfma_f32_16x16x32_bf16 v[104:107], v[174:177], v[220:223], v[104:107]
	v_mfma_f32_16x16x32_bf16 v[100:103], v[204:207], v[220:223], v[100:103]
	v_mfma_f32_16x16x32_bf16 v[88:91], v[174:177], v[228:231], v[88:91]
	v_mfma_f32_16x16x32_bf16 v[84:87], v[204:207], v[228:231], v[84:87]
	v_mfma_f32_16x16x32_bf16 v[72:75], v[174:177], v[236:239], v[72:75]
	v_mfma_f32_16x16x32_bf16 v[68:71], v[204:207], v[236:239], v[68:71]
	s_setprio 3
	s_barrier
	s_add_i32 s34, s64, s46
	s_mov_b32 m0, s34
	ds_read_b128 v[208:211], v179 offset:16384
	ds_read_b128 v[212:215], v179 offset:17408
	ds_read_b128 v[216:219], v179 offset:18432
	ds_read_b128 v[220:223], v179 offset:19456
	ds_read_b128 v[224:227], v179 offset:20480
	ds_read_b128 v[228:231], v179 offset:21504
	ds_read_b128 v[232:235], v179 offset:22528
	ds_read_b128 v[236:239], v179 offset:23552
	global_load_lds_dwordx4 v2, s[38:39]
	s_add_i32 m0, s34, 0x2000
	s_add_u32 s34, s38, 0x158000
	s_addc_u32 s35, s39, 0
	s_add_i32 s64, s65, s46
	global_load_lds_dwordx4 v132, s[38:39]
	s_mov_b32 m0, s64
	s_nop 0
	global_load_lds_dwordx4 v2, s[34:35]
	s_add_i32 m0, s64, 0x2000
	s_nop 0
	global_load_lds_dwordx4 v132, s[34:35]
	s_mov_b32 m0, s47
	s_nop 0
	global_load_lds_dwordx4 v2, s[40:41]
	s_mov_b32 m0, s48
	s_nop 0
	global_load_lds_dwordx4 v132, s[40:41]
	s_nop 0
	s_waitcnt vmcnt(8) lgkmcnt(0)
	s_barrier
	s_setprio 0
	s_waitcnt lgkmcnt(0)
	v_mfma_f32_16x16x32_bf16 v[64:67], v[142:145], v[208:211], v[64:67]
	v_mfma_f32_16x16x32_bf16 v[60:63], v[150:153], v[208:211], v[60:63]
	v_mfma_f32_16x16x32_bf16 v[48:51], v[142:145], v[216:219], v[48:51]
	v_mfma_f32_16x16x32_bf16 v[44:47], v[150:153], v[216:219], v[44:47]
	v_mfma_f32_16x16x32_bf16 v[32:35], v[142:145], v[224:227], v[32:35]
	v_mfma_f32_16x16x32_bf16 v[28:31], v[150:153], v[224:227], v[28:31]
	v_mfma_f32_16x16x32_bf16 v[16:19], v[142:145], v[232:235], v[16:19]
	v_mfma_f32_16x16x32_bf16 v[12:15], v[150:153], v[232:235], v[12:15]
	v_mfma_f32_16x16x32_bf16 v[64:67], v[146:149], v[212:215], v[64:67]
	v_mfma_f32_16x16x32_bf16 v[60:63], v[154:157], v[212:215], v[60:63]
	v_mfma_f32_16x16x32_bf16 v[48:51], v[146:149], v[220:223], v[48:51]
	v_mfma_f32_16x16x32_bf16 v[44:47], v[154:157], v[220:223], v[44:47]
	v_mfma_f32_16x16x32_bf16 v[32:35], v[146:149], v[228:231], v[32:35]
	v_mfma_f32_16x16x32_bf16 v[28:31], v[154:157], v[228:231], v[28:31]
	v_mfma_f32_16x16x32_bf16 v[16:19], v[146:149], v[236:239], v[16:19]
	v_mfma_f32_16x16x32_bf16 v[12:15], v[154:157], v[236:239], v[12:15]
	v_mfma_f32_16x16x32_bf16 v[56:59], v[158:161], v[208:211], v[56:59]
	v_mfma_f32_16x16x32_bf16 v[52:55], v[180:183], v[208:211], v[52:55]
	v_mfma_f32_16x16x32_bf16 v[40:43], v[158:161], v[216:219], v[40:43]
	v_mfma_f32_16x16x32_bf16 v[36:39], v[180:183], v[216:219], v[36:39]
	v_mfma_f32_16x16x32_bf16 v[24:27], v[158:161], v[224:227], v[24:27]
	v_mfma_f32_16x16x32_bf16 v[20:23], v[180:183], v[224:227], v[20:23]
	v_mfma_f32_16x16x32_bf16 v[8:11], v[158:161], v[232:235], v[8:11]
	v_mfma_f32_16x16x32_bf16 v[4:7], v[180:183], v[232:235], v[4:7]
	v_mfma_f32_16x16x32_bf16 v[56:59], v[174:177], v[212:215], v[56:59]
	v_mfma_f32_16x16x32_bf16 v[52:55], v[204:207], v[212:215], v[52:55]
	v_mfma_f32_16x16x32_bf16 v[40:43], v[174:177], v[220:223], v[40:43]
	v_mfma_f32_16x16x32_bf16 v[36:39], v[204:207], v[220:223], v[36:39]
	v_mfma_f32_16x16x32_bf16 v[24:27], v[174:177], v[228:231], v[24:27]
	v_mfma_f32_16x16x32_bf16 v[20:23], v[204:207], v[228:231], v[20:23]
	v_mfma_f32_16x16x32_bf16 v[8:11], v[174:177], v[236:239], v[8:11]
	v_mfma_f32_16x16x32_bf16 v[4:7], v[204:207], v[236:239], v[4:7]
	s_setprio 3
	s_barrier
; #define PG8_STAGE(bufoff, gbase, voff) do { _Pragma("unroll") for (int _i = 0; _i < 2; ++_i) \
;         __builtin_amdgcn_global_load_lds((const unsigned*)((const char*)(gbase) + (voff)[_i]), (PG8_LAS unsigned*)(lds + (bufoff) + ldsw + _i * 8192), 16, 0, 0); } while (0)
; #define PG8_LDA(dst, b, h) do { _Pragma("unroll") for (int m = 0; m < 4; ++m) _Pragma("unroll") for (int k = 0; k < 2; ++k) dst[m][k] = *(const PG8_LAS bf16x8*)(lds + PG8_SA(b, h) + aoff + m * 2048 + k * 1024); } while (0)
; #define PG8_LDB(dst, b, h) do { _Pragma("unroll") for (int n = 0; n < 2; ++n) _Pragma("unroll") for (int k = 0; k < 2; ++k) dst[n][k] = *(const PG8_LAS bf16x8*)(lds + PG8_SB(b, h) + boff + n * 2048 + k * 1024); } while (0)
; #define PG8_MMA(ai, bj, At, Bt) do { __builtin_amdgcn_s_setprio(1); _Pragma("unroll") for (int m = 0; m < 4; ++m) _Pragma("unroll") for (int n = 0; n < 2; ++n) _Pragma("unroll") for (int k = 0; k < 2; ++k) \
;         acc[ai][bj][m][n] = __builtin_amdgcn_mfma_f32_16x16x32_bf16(Bt[n][k], At[m][k], acc[ai][bj][m][n], 0, 0, 0); __builtin_amdgcn_s_setprio(0); } while (0)
; #define PG8_WAIT_V(n) asm volatile("s_waitcnt vmcnt(" #n ")" ::: "memory")
; #define PG8_WAIT_L(n) asm volatile("s_waitcnt lgkmcnt(" #n ")" ::: "memory")
; #define PG8_BAR __builtin_amdgcn_s_barrier()
; #define PG8_SCHED __builtin_amdgcn_sched_barrier(0)
; template <class Epi, class Sched, bool ALIGN_EPI = false, bool SP2 = false>
; __device__ __forceinline__ void gemm_phase(PG8_LAS unsigned char* lds, const Gemm g, const Sched& S, const Epi& E) {
;     ...
;             PG8_LDB(B0, 1, 0); PG8_LDB(B1, 1, 1); PG8_SCHED; PG8_LDA(At, 1, 0); PG8_STAGE(PG8_SA(0, 1), a2 + hstep, voffA);
;             PG8_WAIT_V(8); PG8_WAIT_L(0); PG8_BAR; PG8_MMA(0, 0, At, B0); PG8_MMA(0, 1, At, B1); PG8_BAR; PG8_SCHED;
;             PG8_LDA(At, 1, 1); PG8_STAGE(PG8_SB(1, 0), b3, voffB); PG8_STAGE(PG8_SB(1, 1), b3 + hstep, voffB); PG8_STAGE(PG8_SA(1, 0), a3, voffA);
;             PG8_WAIT_V(8); PG8_WAIT_L(0); PG8_BAR; PG8_MMA(1, 0, At, B0); PG8_MMA(1, 1, At, B1); PG8_BAR; PG8_SCHED;
	s_add_i32 s64, 0, 0x18000
	v_add_u32_e32 v135, s64, v173
	s_add_i32 s65, 0, 0x1c000
	ds_read_b128 v[142:145], v135
	ds_read_b128 v[146:149], v135 offset:1024
	ds_read_b128 v[150:153], v135 offset:2048
	ds_read_b128 v[154:157], v135 offset:3072
	v_add_u32_e32 v135, s65, v173
	ds_read_b128 v[158:161], v135
	ds_read_b128 v[174:177], v135 offset:1024
	ds_read_b128 v[180:183], v135 offset:2048
	ds_read_b128 v[204:207], v135 offset:3072
	s_add_u32 s34, s40, 0x158000
	s_addc_u32 s35, s41, 0
	s_mov_b32 m0, s49
	ds_read_b128 v[208:211], v179 offset:32768
	ds_read_b128 v[212:215], v179 offset:33792
	ds_read_b128 v[216:219], v179 offset:34816
	ds_read_b128 v[220:223], v179 offset:35840
	ds_read_b128 v[224:227], v179 offset:36864
	ds_read_b128 v[228:231], v179 offset:37888
	ds_read_b128 v[232:235], v179 offset:38912
	ds_read_b128 v[236:239], v179 offset:39936
	global_load_lds_dwordx4 v2, s[34:35]
	s_mov_b32 m0, s50
	s_nop 0
	global_load_lds_dwordx4 v132, s[34:35]
	s_waitcnt vmcnt(8) lgkmcnt(0)
	s_barrier
	s_setprio 0
	s_waitcnt lgkmcnt(0)
	v_mfma_f32_16x16x32_bf16 v[128:131], v[142:145], v[208:211], v[128:131]
	v_mfma_f32_16x16x32_bf16 v[124:127], v[150:153], v[208:211], v[124:127]
	v_mfma_f32_16x16x32_bf16 v[112:115], v[142:145], v[216:219], v[112:115]
	v_mfma_f32_16x16x32_bf16 v[108:111], v[150:153], v[216:219], v[108:111]
	v_mfma_f32_16x16x32_bf16 v[96:99], v[142:145], v[224:227], v[96:99]
	v_mfma_f32_16x16x32_bf16 v[92:95], v[150:153], v[224:227], v[92:95]
	v_mfma_f32_16x16x32_bf16 v[80:83], v[142:145], v[232:235], v[80:83]
	v_mfma_f32_16x16x32_bf16 v[76:79], v[150:153], v[232:235], v[76:79]
	v_mfma_f32_16x16x32_bf16 v[128:131], v[146:149], v[212:215], v[128:131]
	v_mfma_f32_16x16x32_bf16 v[124:127], v[154:157], v[212:215], v[124:127]
	v_mfma_f32_16x16x32_bf16 v[112:115], v[146:149], v[220:223], v[112:115]
	v_mfma_f32_16x16x32_bf16 v[108:111], v[154:157], v[220:223], v[108:111]
	v_mfma_f32_16x16x32_bf16 v[96:99], v[146:149], v[228:231], v[96:99]
	v_mfma_f32_16x16x32_bf16 v[92:95], v[154:157], v[228:231], v[92:95]
	v_mfma_f32_16x16x32_bf16 v[80:83], v[146:149], v[236:239], v[80:83]
	v_mfma_f32_16x16x32_bf16 v[76:79], v[154:157], v[236:239], v[76:79]
	v_mfma_f32_16x16x32_bf16 v[120:123], v[158:161], v[208:211], v[120:123]
	v_mfma_f32_16x16x32_bf16 v[116:119], v[180:183], v[208:211], v[116:119]
	v_mfma_f32_16x16x32_bf16 v[104:107], v[158:161], v[216:219], v[104:107]
	v_mfma_f32_16x16x32_bf16 v[100:103], v[180:183], v[216:219], v[100:103]
	v_mfma_f32_16x16x32_bf16 v[88:91], v[158:161], v[224:227], v[88:91]
	v_mfma_f32_16x16x32_bf16 v[84:87], v[180:183], v[224:227], v[84:87]
	v_mfma_f32_16x16x32_bf16 v[72:75], v[158:161], v[232:235], v[72:75]
	v_mfma_f32_16x16x32_bf16 v[68:71], v[180:183], v[232:235], v[68:71]
	v_mfma_f32_16x16x32_bf16 v[120:123], v[174:177], v[212:215], v[120:123]
	v_mfma_f32_16x16x32_bf16 v[116:119], v[204:207], v[212:215], v[116:119]
	v_mfma_f32_16x16x32_bf16 v[104:107], v[174:177], v[220:223], v[104:107]
	v_mfma_f32_16x16x32_bf16 v[100:103], v[204:207], v[220:223], v[100:103]
	v_mfma_f32_16x16x32_bf16 v[88:91], v[174:177], v[228:231], v[88:91]
	v_mfma_f32_16x16x32_bf16 v[84:87], v[204:207], v[228:231], v[84:87]
	v_mfma_f32_16x16x32_bf16 v[72:75], v[174:177], v[236:239], v[72:75]
	v_mfma_f32_16x16x32_bf16 v[68:71], v[204:207], v[236:239], v[68:71]
	s_setprio 3
	s_barrier
	s_add_i32 s34, s64, s46
	s_add_i32 m0, s34, 0xffffff80
	ds_read_b128 v[208:211], v179 offset:49152
	ds_read_b128 v[212:215], v179 offset:50176
	ds_read_b128 v[216:219], v179 offset:51200
	ds_read_b128 v[220:223], v179 offset:52224
	ds_read_b128 v[224:227], v179 offset:53248
	ds_read_b128 v[228:231], v179 offset:54272
	ds_read_b128 v[232:235], v179 offset:55296
	ds_read_b128 v[236:239], v179 offset:56320
	global_load_lds_dwordx4 v2, s[38:39] offset:128
	s_add_i32 m0, s34, 0x1f80
	s_add_u32 s34, s38, 0x158080
	s_addc_u32 s35, s39, 0
	global_load_lds_dwordx4 v132, s[38:39] offset:128
	s_add_i32 s38, s65, s46
	s_mov_b32 m0, s38
	s_nop 0
	global_load_lds_dwordx4 v2, s[34:35]
	s_add_i32 m0, s38, 0x2000
	s_nop 0
	global_load_lds_dwordx4 v132, s[34:35]
	s_add_i32 m0, s53, 0xffffff80
	s_nop 0
	global_load_lds_dwordx4 v2, s[40:41] offset:128
	s_add_i32 m0, s54, 0xffffff80
	s_nop 0
	global_load_lds_dwordx4 v132, s[40:41] offset:128
	s_waitcnt vmcnt(8) lgkmcnt(0)
	s_barrier
	s_setprio 0
	s_waitcnt lgkmcnt(0)
	v_mfma_f32_16x16x32_bf16 v[64:67], v[142:145], v[208:211], v[64:67]
	v_mfma_f32_16x16x32_bf16 v[60:63], v[150:153], v[208:211], v[60:63]
	v_mfma_f32_16x16x32_bf16 v[48:51], v[142:145], v[216:219], v[48:51]
	v_mfma_f32_16x16x32_bf16 v[44:47], v[150:153], v[216:219], v[44:47]
	v_mfma_f32_16x16x32_bf16 v[32:35], v[142:145], v[224:227], v[32:35]
	v_mfma_f32_16x16x32_bf16 v[28:31], v[150:153], v[224:227], v[28:31]
	v_mfma_f32_16x16x32_bf16 v[16:19], v[142:145], v[232:235], v[16:19]
	v_mfma_f32_16x16x32_bf16 v[12:15], v[150:153], v[232:235], v[12:15]
	v_mfma_f32_16x16x32_bf16 v[64:67], v[146:149], v[212:215], v[64:67]
	v_mfma_f32_16x16x32_bf16 v[60:63], v[154:157], v[212:215], v[60:63]
	v_mfma_f32_16x16x32_bf16 v[48:51], v[146:149], v[220:223], v[48:51]
	v_mfma_f32_16x16x32_bf16 v[44:47], v[154:157], v[220:223], v[44:47]
	v_mfma_f32_16x16x32_bf16 v[32:35], v[146:149], v[228:231], v[32:35]
	v_mfma_f32_16x16x32_bf16 v[28:31], v[154:157], v[228:231], v[28:31]
	v_mfma_f32_16x16x32_bf16 v[16:19], v[146:149], v[236:239], v[16:19]
	v_mfma_f32_16x16x32_bf16 v[12:15], v[154:157], v[236:239], v[12:15]
	v_mfma_f32_16x16x32_bf16 v[56:59], v[158:161], v[208:211], v[56:59]
	v_mfma_f32_16x16x32_bf16 v[52:55], v[180:183], v[208:211], v[52:55]
	v_mfma_f32_16x16x32_bf16 v[40:43], v[158:161], v[216:219], v[40:43]
	v_mfma_f32_16x16x32_bf16 v[36:39], v[180:183], v[216:219], v[36:39]
	v_mfma_f32_16x16x32_bf16 v[24:27], v[158:161], v[224:227], v[24:27]
	v_mfma_f32_16x16x32_bf16 v[20:23], v[180:183], v[224:227], v[20:23]
	v_mfma_f32_16x16x32_bf16 v[8:11], v[158:161], v[232:235], v[8:11]
	v_mfma_f32_16x16x32_bf16 v[4:7], v[180:183], v[232:235], v[4:7]
	v_mfma_f32_16x16x32_bf16 v[56:59], v[174:177], v[212:215], v[56:59]
	v_mfma_f32_16x16x32_bf16 v[52:55], v[204:207], v[212:215], v[52:55]
	v_mfma_f32_16x16x32_bf16 v[40:43], v[174:177], v[220:223], v[40:43]
	v_mfma_f32_16x16x32_bf16 v[36:39], v[204:207], v[220:223], v[36:39]
	v_mfma_f32_16x16x32_bf16 v[24:27], v[174:177], v[228:231], v[24:27]
	v_mfma_f32_16x16x32_bf16 v[20:23], v[204:207], v[228:231], v[20:23]
	v_mfma_f32_16x16x32_bf16 v[8:11], v[174:177], v[236:239], v[8:11]
	v_mfma_f32_16x16x32_bf16 v[4:7], v[204:207], v[236:239], v[4:7]
	s_setprio 3
	s_barrier
	s_add_i32 s63, s63, 2
	s_add_u32 s61, s61, 0x100
	s_addc_u32 s62, s62, 0
	s_cmpk_gt_u32 s63, 0x53
	s_mov_b64 s[34:35], s[36:37]
	s_cbranch_scc0 .LBB0_575
	s_and_b64 vcc, exec, s[28:29]
	s_cbranch_vccz .LBB0_578
	s_barrier

; #define PG8_STAGE(bufoff, gbase, voff) do { _Pragma("unroll") for (int _i = 0; _i < 2; ++_i) \
;         __builtin_amdgcn_global_load_lds((const unsigned*)((const char*)(gbase) + (voff)[_i]), (PG8_LAS unsigned*)(lds + (bufoff) + ldsw + _i * 8192), 16, 0, 0); } while (0)
; #define PG8_LDA(dst, b, h) do { _Pragma("unroll") for (int m = 0; m < 4; ++m) _Pragma("unroll") for (int k = 0; k < 2; ++k) dst[m][k] = *(const PG8_LAS bf16x8*)(lds + PG8_SA(b, h) + aoff + m * 2048 + k * 1024); } while (0)
; #define PG8_LDB(dst, b, h) do { _Pragma("unroll") for (int n = 0; n < 2; ++n) _Pragma("unroll") for (int k = 0; k < 2; ++k) dst[n][k] = *(const PG8_LAS bf16x8*)(lds + PG8_SB(b, h) + boff + n * 2048 + k * 1024); } while (0)
; #define PG8_MMA(ai, bj, At, Bt) do { __builtin_amdgcn_s_setprio(1); _Pragma("unroll") for (int m = 0; m < 4; ++m) _Pragma("unroll") for (int n = 0; n < 2; ++n) _Pragma("unroll") for (int k = 0; k < 2; ++k) \
;         acc[ai][bj][m][n] = __builtin_amdgcn_mfma_f32_16x16x32_bf16(Bt[n][k], At[m][k], acc[ai][bj][m][n], 0, 0, 0); __builtin_amdgcn_s_setprio(0); } while (0)
; #define PG8_WAIT_V(n) asm volatile("s_waitcnt vmcnt(" #n ")" ::: "memory")
; #define PG8_WAIT_L(n) asm volatile("s_waitcnt lgkmcnt(" #n ")" ::: "memory")
; template <class Epi, class Sched, bool ALIGN_EPI = false, bool SP2 = false>
; __device__ __forceinline__ void gemm_phase(PG8_LAS unsigned char* lds, const Gemm g, const Sched& S, const Epi& E) {
;     ...
;             const bool last = (t == nt - 2);
;             const char* a1 = cA + (size_t)(t + 1) * kstep;
;             const char* a2 = last ? nA : cA + (size_t)(t + 2) * kstep; const char* b2 = last ? nB : cB + (size_t)(t + 2) * kstep;
;             const char* a3 = a2 + kstep; const char* b3 = b2 + kstep;
;             if (last && has_next) S.a_ready(nxt);
;             if constexpr (SP2) {
;             PG8_LDB(B0, 0, 0); PG8_LDB(B1, 0, 1); PG8_SCHED; PG8_LDA(At, 0, 0); PG8_STAGE(PG8_SA(1, 1), a1 + hstep, voffA);
;             PG8_WAIT_V(8); PG8_WAIT_L(0); PG8_BAR; PG8_MMA(0, 0, At, B0); PG8_MMA(0, 1, At, B1); PG8_BAR; PG8_SCHED;
;             PG8_LDA(At, 0, 1); PG8_STAGE(PG8_SB(0, 0), b2, voffB); PG8_STAGE(PG8_SB(0, 1), b2 + hstep, voffB); PG8_STAGE(PG8_SA(0, 0), a2, voffA);
;             PG8_WAIT_V(8); PG8_WAIT_L(0); PG8_BAR; PG8_MMA(1, 0, At, B0); PG8_MMA(1, 1, At, B1); PG8_BAR; PG8_SCHED;
.LBB0_674:
	s_add_u32 s42, s40, 0xfff80080
	s_addc_u32 s43, s41, -1
	s_add_i32 s64, 0, 0x10000
	s_cmp_eq_u32 s63, 28
	s_cselect_b32 s45, s5, s43
	s_cselect_b32 s44, s4, s42
	s_cselect_b32 s43, s37, s62
	s_cselect_b32 s42, s36, s35
	s_add_i32 s66, 0, 0x14000
	v_add_u32_e32 v144, s64, v173
	v_add_u32_e32 v162, s66, v173
	ds_read_b128 v[132:135], v144
	ds_read_b128 v[136:139], v144 offset:1024
	ds_read_b128 v[140:143], v144 offset:2048
	ds_read_b128 v[144:147], v144 offset:3072
	ds_read_b128 v[158:161], v162
	ds_read_b128 v[174:177], v162 offset:1024
	ds_read_b128 v[206:209], v162 offset:2048
	ds_read_b128 v[210:213], v162 offset:3072
	s_add_i32 m0, s39, 0xc000
	ds_read_b128 v[214:217], v204
	ds_read_b128 v[218:221], v204 offset:1024
	ds_read_b128 v[222:225], v204 offset:2048
	ds_read_b128 v[226:229], v204 offset:3072
	ds_read_b128 v[230:233], v204 offset:4096
	ds_read_b128 v[234:237], v204 offset:5120
	ds_read_b128 v[238:241], v204 offset:6144
	ds_read_b128 v[242:245], v204 offset:7168
	global_load_lds_dwordx4 v154, s[40:41]
	s_add_i32 m0, s39, 0xe000
	s_nop 0
	global_load_lds_dwordx4 v156, s[40:41]
	s_nop 0
	s_waitcnt vmcnt(8) lgkmcnt(0)
	s_barrier
	s_setprio 0
	s_waitcnt lgkmcnt(0)
	v_mfma_f32_16x16x32_bf16 v[128:131], v[132:135], v[214:217], v[128:131]
	v_mfma_f32_16x16x32_bf16 v[124:127], v[140:143], v[214:217], v[124:127]
	v_mfma_f32_16x16x32_bf16 v[116:119], v[132:135], v[222:225], v[116:119]
	v_mfma_f32_16x16x32_bf16 v[108:111], v[140:143], v[222:225], v[108:111]
	v_mfma_f32_16x16x32_bf16 v[100:103], v[132:135], v[230:233], v[100:103]
	v_mfma_f32_16x16x32_bf16 v[92:95], v[140:143], v[230:233], v[92:95]
	v_mfma_f32_16x16x32_bf16 v[84:87], v[132:135], v[238:241], v[84:87]
	v_mfma_f32_16x16x32_bf16 v[76:79], v[140:143], v[238:241], v[76:79]
	v_mfma_f32_16x16x32_bf16 v[128:131], v[136:139], v[218:221], v[128:131]
	v_mfma_f32_16x16x32_bf16 v[124:127], v[144:147], v[218:221], v[124:127]
	v_mfma_f32_16x16x32_bf16 v[116:119], v[136:139], v[226:229], v[116:119]
	v_mfma_f32_16x16x32_bf16 v[108:111], v[144:147], v[226:229], v[108:111]
	v_mfma_f32_16x16x32_bf16 v[100:103], v[136:139], v[234:237], v[100:103]
	v_mfma_f32_16x16x32_bf16 v[92:95], v[144:147], v[234:237], v[92:95]
	v_mfma_f32_16x16x32_bf16 v[84:87], v[136:139], v[242:245], v[84:87]
	v_mfma_f32_16x16x32_bf16 v[76:79], v[144:147], v[242:245], v[76:79]
	v_mfma_f32_16x16x32_bf16 v[120:123], v[158:161], v[214:217], v[120:123]
	v_mfma_f32_16x16x32_bf16 v[112:115], v[206:209], v[214:217], v[112:115]
	v_mfma_f32_16x16x32_bf16 v[104:107], v[158:161], v[222:225], v[104:107]
	v_mfma_f32_16x16x32_bf16 v[96:99], v[206:209], v[222:225], v[96:99]
	v_mfma_f32_16x16x32_bf16 v[88:91], v[158:161], v[230:233], v[88:91]
	v_mfma_f32_16x16x32_bf16 v[80:83], v[206:209], v[230:233], v[80:83]
	v_mfma_f32_16x16x32_bf16 v[72:75], v[158:161], v[238:241], v[72:75]
	v_mfma_f32_16x16x32_bf16 v[68:71], v[206:209], v[238:241], v[68:71]
	v_mfma_f32_16x16x32_bf16 v[120:123], v[174:177], v[218:221], v[120:123]
	v_mfma_f32_16x16x32_bf16 v[112:115], v[210:213], v[218:221], v[112:115]
	v_mfma_f32_16x16x32_bf16 v[104:107], v[174:177], v[226:229], v[104:107]
	v_mfma_f32_16x16x32_bf16 v[96:99], v[210:213], v[226:229], v[96:99]
	v_mfma_f32_16x16x32_bf16 v[88:91], v[174:177], v[234:237], v[88:91]
	v_mfma_f32_16x16x32_bf16 v[80:83], v[210:213], v[234:237], v[80:83]
	v_mfma_f32_16x16x32_bf16 v[72:75], v[174:177], v[242:245], v[72:75]
	v_mfma_f32_16x16x32_bf16 v[68:71], v[210:213], v[242:245], v[68:71]
	s_setprio 3
	s_barrier
	s_add_i32 s64, s64, s46
	s_mov_b32 m0, s64
	ds_read_b128 v[214:217], v204 offset:16384
	ds_read_b128 v[218:221], v204 offset:17408
	ds_read_b128 v[222:225], v204 offset:18432
	ds_read_b128 v[226:229], v204 offset:19456
	ds_read_b128 v[230:233], v204 offset:20480
	ds_read_b128 v[234:237], v204 offset:21504
	ds_read_b128 v[238:241], v204 offset:22528
	ds_read_b128 v[242:245], v204 offset:23552
	global_load_lds_dwordx4 v2, s[42:43]
	s_add_i32 m0, s64, 0x2000
	s_add_u32 s64, s42, 0x80000
	s_addc_u32 s65, s43, 0
	s_add_i32 s66, s66, s46
	global_load_lds_dwordx4 v148, s[42:43]
	s_mov_b32 m0, s66
	s_nop 0
	global_load_lds_dwordx4 v2, s[64:65]
	s_add_i32 m0, s66, 0x2000
	s_nop 0
	global_load_lds_dwordx4 v148, s[64:65]
	s_mov_b32 m0, s39
	s_nop 0
	global_load_lds_dwordx4 v152, s[44:45]
	s_mov_b32 m0, s51
	s_nop 0
	global_load_lds_dwordx4 v150, s[44:45]
	s_nop 0
	s_waitcnt vmcnt(8) lgkmcnt(0)
	s_barrier
	s_setprio 0
	s_waitcnt lgkmcnt(0)
	v_mfma_f32_16x16x32_bf16 v[64:67], v[132:135], v[214:217], v[64:67]
	v_mfma_f32_16x16x32_bf16 v[60:63], v[140:143], v[214:217], v[60:63]
	v_mfma_f32_16x16x32_bf16 v[52:55], v[132:135], v[222:225], v[52:55]
	v_mfma_f32_16x16x32_bf16 v[44:47], v[140:143], v[222:225], v[44:47]
	v_mfma_f32_16x16x32_bf16 v[36:39], v[132:135], v[230:233], v[36:39]
	v_mfma_f32_16x16x32_bf16 v[28:31], v[140:143], v[230:233], v[28:31]
	v_mfma_f32_16x16x32_bf16 v[20:23], v[132:135], v[238:241], v[20:23]
	v_mfma_f32_16x16x32_bf16 v[12:15], v[140:143], v[238:241], v[12:15]
	v_mfma_f32_16x16x32_bf16 v[64:67], v[136:139], v[218:221], v[64:67]
	v_mfma_f32_16x16x32_bf16 v[60:63], v[144:147], v[218:221], v[60:63]
	v_mfma_f32_16x16x32_bf16 v[52:55], v[136:139], v[226:229], v[52:55]
	v_mfma_f32_16x16x32_bf16 v[44:47], v[144:147], v[226:229], v[44:47]
	v_mfma_f32_16x16x32_bf16 v[36:39], v[136:139], v[234:237], v[36:39]
	v_mfma_f32_16x16x32_bf16 v[28:31], v[144:147], v[234:237], v[28:31]
	v_mfma_f32_16x16x32_bf16 v[20:23], v[136:139], v[242:245], v[20:23]
	v_mfma_f32_16x16x32_bf16 v[12:15], v[144:147], v[242:245], v[12:15]
	v_mfma_f32_16x16x32_bf16 v[56:59], v[158:161], v[214:217], v[56:59]
	v_mfma_f32_16x16x32_bf16 v[48:51], v[206:209], v[214:217], v[48:51]
	v_mfma_f32_16x16x32_bf16 v[40:43], v[158:161], v[222:225], v[40:43]
	v_mfma_f32_16x16x32_bf16 v[32:35], v[206:209], v[222:225], v[32:35]
	v_mfma_f32_16x16x32_bf16 v[24:27], v[158:161], v[230:233], v[24:27]
	v_mfma_f32_16x16x32_bf16 v[16:19], v[206:209], v[230:233], v[16:19]
	v_mfma_f32_16x16x32_bf16 v[8:11], v[158:161], v[238:241], v[8:11]
	v_mfma_f32_16x16x32_bf16 v[4:7], v[206:209], v[238:241], v[4:7]
	v_mfma_f32_16x16x32_bf16 v[56:59], v[174:177], v[218:221], v[56:59]
	v_mfma_f32_16x16x32_bf16 v[48:51], v[210:213], v[218:221], v[48:51]
	v_mfma_f32_16x16x32_bf16 v[40:43], v[174:177], v[226:229], v[40:43]
	v_mfma_f32_16x16x32_bf16 v[32:35], v[210:213], v[226:229], v[32:35]
	v_mfma_f32_16x16x32_bf16 v[24:27], v[174:177], v[234:237], v[24:27]
	v_mfma_f32_16x16x32_bf16 v[16:19], v[210:213], v[234:237], v[16:19]
	v_mfma_f32_16x16x32_bf16 v[8:11], v[174:177], v[242:245], v[8:11]
	v_mfma_f32_16x16x32_bf16 v[4:7], v[210:213], v[242:245], v[4:7]
	s_setprio 3
	s_barrier
; #define PG8_STAGE(bufoff, gbase, voff) do { _Pragma("unroll") for (int _i = 0; _i < 2; ++_i) \
;         __builtin_amdgcn_global_load_lds((const unsigned*)((const char*)(gbase) + (voff)[_i]), (PG8_LAS unsigned*)(lds + (bufoff) + ldsw + _i * 8192), 16, 0, 0); } while (0)
; #define PG8_LDA(dst, b, h) do { _Pragma("unroll") for (int m = 0; m < 4; ++m) _Pragma("unroll") for (int k = 0; k < 2; ++k) dst[m][k] = *(const PG8_LAS bf16x8*)(lds + PG8_SA(b, h) + aoff + m * 2048 + k * 1024); } while (0)
; #define PG8_LDB(dst, b, h) do { _Pragma("unroll") for (int n = 0; n < 2; ++n) _Pragma("unroll") for (int k = 0; k < 2; ++k) dst[n][k] = *(const PG8_LAS bf16x8*)(lds + PG8_SB(b, h) + boff + n * 2048 + k * 1024); } while (0)
; #define PG8_MMA(ai, bj, At, Bt) do { __builtin_amdgcn_s_setprio(1); _Pragma("unroll") for (int m = 0; m < 4; ++m) _Pragma("unroll") for (int n = 0; n < 2; ++n) _Pragma("unroll") for (int k = 0; k < 2; ++k) \
;         acc[ai][bj][m][n] = __builtin_amdgcn_mfma_f32_16x16x32_bf16(Bt[n][k], At[m][k], acc[ai][bj][m][n], 0, 0, 0); __builtin_amdgcn_s_setprio(0); } while (0)
; #define PG8_WAIT_V(n) asm volatile("s_waitcnt vmcnt(" #n ")" ::: "memory")
; #define PG8_WAIT_L(n) asm volatile("s_waitcnt lgkmcnt(" #n ")" ::: "memory")
; #define PG8_BAR __builtin_amdgcn_s_barrier()
; #define PG8_SCHED __builtin_amdgcn_sched_barrier(0)
; template <class Epi, class Sched, bool ALIGN_EPI = false, bool SP2 = false>
; __device__ __forceinline__ void gemm_phase(PG8_LAS unsigned char* lds, const Gemm g, const Sched& S, const Epi& E) {
;     ...
;             PG8_LDB(B0, 1, 0); PG8_LDB(B1, 1, 1); PG8_SCHED; PG8_LDA(At, 1, 0); PG8_STAGE(PG8_SA(0, 1), a2 + hstep, voffA);
;             PG8_WAIT_V(8); PG8_WAIT_L(0); PG8_BAR; PG8_MMA(0, 0, At, B0); PG8_MMA(0, 1, At, B1); PG8_BAR; PG8_SCHED;
;             PG8_LDA(At, 1, 1); PG8_STAGE(PG8_SB(1, 0), b3, voffB); PG8_STAGE(PG8_SB(1, 1), b3 + hstep, voffB); PG8_STAGE(PG8_SA(1, 0), a3, voffA);
;             PG8_WAIT_V(8); PG8_WAIT_L(0); PG8_BAR; PG8_MMA(1, 0, At, B0); PG8_MMA(1, 1, At, B1); PG8_BAR; PG8_SCHED;
	s_add_i32 s64, 0, 0x18000
	s_add_i32 s65, 0, 0x1c000
	v_add_u32_e32 v144, s64, v173
	v_add_u32_e32 v164, s65, v173
	ds_read_b128 v[132:135], v144
	ds_read_b128 v[136:139], v144 offset:1024
	ds_read_b128 v[140:143], v144 offset:2048
	ds_read_b128 v[144:147], v144 offset:3072
	ds_read_b128 v[158:161], v164
	ds_read_b128 v[174:177], v164 offset:1024
	ds_read_b128 v[206:209], v164 offset:2048
	ds_read_b128 v[210:213], v164 offset:3072
	s_add_u32 s100, s44, 0x80
	s_addc_u32 s101, s45, 0
	s_add_u32 s44, s44, 0x80000
	s_addc_u32 s45, s45, 0
	s_mov_b32 m0, s52
	ds_read_b128 v[214:217], v204 offset:32768
	ds_read_b128 v[218:221], v204 offset:33792
	ds_read_b128 v[222:225], v204 offset:34816
	ds_read_b128 v[226:229], v204 offset:35840
	ds_read_b128 v[230:233], v204 offset:36864
	ds_read_b128 v[234:237], v204 offset:37888
	ds_read_b128 v[238:241], v204 offset:38912
	ds_read_b128 v[242:245], v204 offset:39936
	global_load_lds_dwordx4 v152, s[44:45]
	s_mov_b32 m0, s53
	s_nop 0
	global_load_lds_dwordx4 v150, s[44:45]
	s_nop 0
	s_waitcnt vmcnt(8) lgkmcnt(0)
	s_barrier
	s_setprio 0
	s_waitcnt lgkmcnt(0)
	v_mfma_f32_16x16x32_bf16 v[128:131], v[132:135], v[214:217], v[128:131]
	v_mfma_f32_16x16x32_bf16 v[124:127], v[140:143], v[214:217], v[124:127]
	v_mfma_f32_16x16x32_bf16 v[116:119], v[132:135], v[222:225], v[116:119]
	v_mfma_f32_16x16x32_bf16 v[108:111], v[140:143], v[222:225], v[108:111]
	v_mfma_f32_16x16x32_bf16 v[100:103], v[132:135], v[230:233], v[100:103]
	v_mfma_f32_16x16x32_bf16 v[92:95], v[140:143], v[230:233], v[92:95]
	v_mfma_f32_16x16x32_bf16 v[84:87], v[132:135], v[238:241], v[84:87]
	v_mfma_f32_16x16x32_bf16 v[76:79], v[140:143], v[238:241], v[76:79]
	v_mfma_f32_16x16x32_bf16 v[128:131], v[136:139], v[218:221], v[128:131]
	v_mfma_f32_16x16x32_bf16 v[124:127], v[144:147], v[218:221], v[124:127]
	v_mfma_f32_16x16x32_bf16 v[116:119], v[136:139], v[226:229], v[116:119]
	v_mfma_f32_16x16x32_bf16 v[108:111], v[144:147], v[226:229], v[108:111]
	v_mfma_f32_16x16x32_bf16 v[100:103], v[136:139], v[234:237], v[100:103]
	v_mfma_f32_16x16x32_bf16 v[92:95], v[144:147], v[234:237], v[92:95]
	v_mfma_f32_16x16x32_bf16 v[84:87], v[136:139], v[242:245], v[84:87]
	v_mfma_f32_16x16x32_bf16 v[76:79], v[144:147], v[242:245], v[76:79]
	v_mfma_f32_16x16x32_bf16 v[120:123], v[158:161], v[214:217], v[120:123]
	v_mfma_f32_16x16x32_bf16 v[112:115], v[206:209], v[214:217], v[112:115]
	v_mfma_f32_16x16x32_bf16 v[104:107], v[158:161], v[222:225], v[104:107]
	v_mfma_f32_16x16x32_bf16 v[96:99], v[206:209], v[222:225], v[96:99]
	v_mfma_f32_16x16x32_bf16 v[88:91], v[158:161], v[230:233], v[88:91]
	v_mfma_f32_16x16x32_bf16 v[80:83], v[206:209], v[230:233], v[80:83]
	v_mfma_f32_16x16x32_bf16 v[72:75], v[158:161], v[238:241], v[72:75]
	v_mfma_f32_16x16x32_bf16 v[68:71], v[206:209], v[238:241], v[68:71]
	v_mfma_f32_16x16x32_bf16 v[120:123], v[174:177], v[218:221], v[120:123]
	v_mfma_f32_16x16x32_bf16 v[112:115], v[210:213], v[218:221], v[112:115]
	v_mfma_f32_16x16x32_bf16 v[104:107], v[174:177], v[226:229], v[104:107]
	v_mfma_f32_16x16x32_bf16 v[96:99], v[210:213], v[226:229], v[96:99]
	v_mfma_f32_16x16x32_bf16 v[88:91], v[174:177], v[234:237], v[88:91]
	v_mfma_f32_16x16x32_bf16 v[80:83], v[210:213], v[234:237], v[80:83]
	v_mfma_f32_16x16x32_bf16 v[72:75], v[174:177], v[242:245], v[72:75]
	v_mfma_f32_16x16x32_bf16 v[68:71], v[210:213], v[242:245], v[68:71]
	s_setprio 3
	s_barrier
	s_add_i32 s44, s64, s46
	s_add_i32 m0, s44, 0xffffff80
	ds_read_b128 v[214:217], v204 offset:49152
	ds_read_b128 v[218:221], v204 offset:50176
	ds_read_b128 v[222:225], v204 offset:51200
	ds_read_b128 v[226:229], v204 offset:52224
	ds_read_b128 v[230:233], v204 offset:53248
	ds_read_b128 v[234:237], v204 offset:54272
	ds_read_b128 v[238:241], v204 offset:55296
	ds_read_b128 v[242:245], v204 offset:56320
	global_load_lds_dwordx4 v2, s[42:43] offset:128
	s_add_i32 m0, s44, 0x1f80
	s_add_i32 s44, s65, s46
	global_load_lds_dwordx4 v148, s[42:43] offset:128
	s_add_u32 s42, s42, 0x80080
	s_addc_u32 s43, s43, 0
	s_mov_b32 m0, s44
	s_nop 0
	global_load_lds_dwordx4 v2, s[42:43]
	s_add_i32 m0, s44, 0x2000
	s_nop 0
	global_load_lds_dwordx4 v148, s[42:43]
	s_mov_b32 m0, s54
	s_nop 0
	global_load_lds_dwordx4 v152, s[100:101]
	s_mov_b32 m0, s55
	s_nop 0
	global_load_lds_dwordx4 v150, s[100:101]
	s_waitcnt vmcnt(8) lgkmcnt(0)
	s_barrier
	s_setprio 0
	s_waitcnt lgkmcnt(0)
	v_mfma_f32_16x16x32_bf16 v[64:67], v[132:135], v[214:217], v[64:67]
	v_mfma_f32_16x16x32_bf16 v[60:63], v[140:143], v[214:217], v[60:63]
	v_mfma_f32_16x16x32_bf16 v[52:55], v[132:135], v[222:225], v[52:55]
	v_mfma_f32_16x16x32_bf16 v[44:47], v[140:143], v[222:225], v[44:47]
	v_mfma_f32_16x16x32_bf16 v[36:39], v[132:135], v[230:233], v[36:39]
	v_mfma_f32_16x16x32_bf16 v[28:31], v[140:143], v[230:233], v[28:31]
	v_mfma_f32_16x16x32_bf16 v[20:23], v[132:135], v[238:241], v[20:23]
	v_mfma_f32_16x16x32_bf16 v[12:15], v[140:143], v[238:241], v[12:15]
	v_mfma_f32_16x16x32_bf16 v[64:67], v[136:139], v[218:221], v[64:67]
	v_mfma_f32_16x16x32_bf16 v[60:63], v[144:147], v[218:221], v[60:63]
	v_mfma_f32_16x16x32_bf16 v[52:55], v[136:139], v[226:229], v[52:55]
	v_mfma_f32_16x16x32_bf16 v[44:47], v[144:147], v[226:229], v[44:47]
	v_mfma_f32_16x16x32_bf16 v[36:39], v[136:139], v[234:237], v[36:39]
	v_mfma_f32_16x16x32_bf16 v[28:31], v[144:147], v[234:237], v[28:31]
	v_mfma_f32_16x16x32_bf16 v[20:23], v[136:139], v[242:245], v[20:23]
	v_mfma_f32_16x16x32_bf16 v[12:15], v[144:147], v[242:245], v[12:15]
	v_mfma_f32_16x16x32_bf16 v[56:59], v[158:161], v[214:217], v[56:59]
	v_mfma_f32_16x16x32_bf16 v[48:51], v[206:209], v[214:217], v[48:51]
	v_mfma_f32_16x16x32_bf16 v[40:43], v[158:161], v[222:225], v[40:43]
	v_mfma_f32_16x16x32_bf16 v[32:35], v[206:209], v[222:225], v[32:35]
	v_mfma_f32_16x16x32_bf16 v[24:27], v[158:161], v[230:233], v[24:27]
	v_mfma_f32_16x16x32_bf16 v[16:19], v[206:209], v[230:233], v[16:19]
	v_mfma_f32_16x16x32_bf16 v[8:11], v[158:161], v[238:241], v[8:11]
	v_mfma_f32_16x16x32_bf16 v[4:7], v[206:209], v[238:241], v[4:7]
	v_mfma_f32_16x16x32_bf16 v[56:59], v[174:177], v[218:221], v[56:59]
	v_mfma_f32_16x16x32_bf16 v[48:51], v[210:213], v[218:221], v[48:51]
	v_mfma_f32_16x16x32_bf16 v[40:43], v[174:177], v[226:229], v[40:43]
	v_mfma_f32_16x16x32_bf16 v[32:35], v[210:213], v[226:229], v[32:35]
	v_mfma_f32_16x16x32_bf16 v[24:27], v[174:177], v[234:237], v[24:27]
	v_mfma_f32_16x16x32_bf16 v[16:19], v[210:213], v[234:237], v[16:19]
	v_mfma_f32_16x16x32_bf16 v[8:11], v[174:177], v[242:245], v[8:11]
	v_mfma_f32_16x16x32_bf16 v[4:7], v[210:213], v[242:245], v[4:7]
	s_setprio 3
	s_barrier
	s_add_i32 s63, s63, 2
	s_add_u32 s40, s40, 0x100
	s_addc_u32 s41, s41, 0
	s_add_u32 s35, s35, 0x100
	s_addc_u32 s62, s62, 0
	s_cmp_gt_u32 s63, 29
	s_cbranch_scc0 .LBB0_674
	s_and_b64 vcc, exec, s[30:31]
	s_cbranch_vccz .LBB0_677
	s_barrier

; #define PG8_STAGE(bufoff, gbase, voff) do { _Pragma("unroll") for (int _i = 0; _i < 2; ++_i) \
;         __builtin_amdgcn_global_load_lds((const unsigned*)((const char*)(gbase) + (voff)[_i]), (PG8_LAS unsigned*)(lds + (bufoff) + ldsw + _i * 8192), 16, 0, 0); } while (0)
; #define PG8_LDA(dst, b, h) do { _Pragma("unroll") for (int m = 0; m < 4; ++m) _Pragma("unroll") for (int k = 0; k < 2; ++k) dst[m][k] = *(const PG8_LAS bf16x8*)(lds + PG8_SA(b, h) + aoff + m * 2048 + k * 1024); } while (0)
; #define PG8_LDB(dst, b, h) do { _Pragma("unroll") for (int n = 0; n < 2; ++n) _Pragma("unroll") for (int k = 0; k < 2; ++k) dst[n][k] = *(const PG8_LAS bf16x8*)(lds + PG8_SB(b, h) + boff + n * 2048 + k * 1024); } while (0)
; #define PG8_MMA(ai, bj, At, Bt) do { __builtin_amdgcn_s_setprio(1); _Pragma("unroll") for (int m = 0; m < 4; ++m) _Pragma("unroll") for (int n = 0; n < 2; ++n) _Pragma("unroll") for (int k = 0; k < 2; ++k) \
;         acc[ai][bj][m][n] = __builtin_amdgcn_mfma_f32_16x16x32_bf16(Bt[n][k], At[m][k], acc[ai][bj][m][n], 0, 0, 0); __builtin_amdgcn_s_setprio(0); } while (0)
; #define PG8_WAIT_V(n) asm volatile("s_waitcnt vmcnt(" #n ")" ::: "memory")
; #define PG8_WAIT_L(n) asm volatile("s_waitcnt lgkmcnt(" #n ")" ::: "memory")
; template <class Epi, class Sched, bool ALIGN_EPI = false, bool SP2 = false>
; __device__ __forceinline__ void gemm_phase(PG8_LAS unsigned char* lds, const Gemm g, const Sched& S, const Epi& E) {
;     ...
;             const bool last = (t == nt - 2);
;             const char* a1 = cA + (size_t)(t + 1) * kstep;
;             const char* a2 = last ? nA : cA + (size_t)(t + 2) * kstep; const char* b2 = last ? nB : cB + (size_t)(t + 2) * kstep;
;             const char* a3 = a2 + kstep; const char* b3 = b2 + kstep;
;             if (last && has_next) S.a_ready(nxt);
;             if constexpr (SP2) {
;             PG8_LDB(B0, 0, 0); PG8_LDB(B1, 0, 1); PG8_SCHED; PG8_LDA(At, 0, 0); PG8_STAGE(PG8_SA(1, 1), a1 + hstep, voffA);
;             PG8_WAIT_V(8); PG8_WAIT_L(0); PG8_BAR; PG8_MMA(0, 0, At, B0); PG8_MMA(0, 1, At, B1); PG8_BAR; PG8_SCHED;
;             PG8_LDA(At, 0, 1); PG8_STAGE(PG8_SB(0, 0), b2, voffB); PG8_STAGE(PG8_SB(0, 1), b2 + hstep, voffB); PG8_STAGE(PG8_SA(0, 0), a2, voffA);
;             PG8_WAIT_V(8); PG8_WAIT_L(0); PG8_BAR; PG8_MMA(1, 0, At, B0); PG8_MMA(1, 1, At, B1); PG8_BAR; PG8_SCHED;
.LBB0_2096:
	s_add_u32 s27, s40, 0xfffc0080
	s_addc_u32 s29, s41, -1
	s_add_i32 s31, 0, 0x10000
	s_cmp_eq_u32 s26, 12
	s_cselect_b32 s45, s1, s29
	s_cselect_b32 s44, s0, s27
	v_add_u32_e32 v2, s31, v173
	s_cselect_b32 s43, s35, s13
	s_cselect_b32 s42, s34, s11
	s_add_i32 s27, 0, 0x14000
	ds_read_b128 v[134:137], v2
	ds_read_b128 v[138:141], v2 offset:1024
	ds_read_b128 v[154:157], v2 offset:2048
	ds_read_b128 v[158:161], v2 offset:3072
	v_add_u32_e32 v2, s27, v173
	ds_read_b128 v[178:181], v2
	ds_read_b128 v[204:207], v2 offset:1024
	ds_read_b128 v[208:211], v2 offset:2048
	ds_read_b128 v[212:215], v2 offset:3072
	s_add_i32 m0, s55, 0xc000
	ds_read_b128 v[216:219], v177
	ds_read_b128 v[220:223], v177 offset:1024
	ds_read_b128 v[224:227], v177 offset:2048
	ds_read_b128 v[228:231], v177 offset:3072
	ds_read_b128 v[232:235], v177 offset:4096
	ds_read_b128 v[236:239], v177 offset:5120
	ds_read_b128 v[240:243], v177 offset:6144
	ds_read_b128 v[244:247], v177 offset:7168
	global_load_lds_dwordx4 v150, s[40:41]
	s_add_i32 m0, s55, 0xe000
	s_nop 0
	global_load_lds_dwordx4 v152, s[40:41]
	s_nop 0
	s_waitcnt vmcnt(8) lgkmcnt(0)
	s_barrier
	s_setprio 0
	s_waitcnt lgkmcnt(0)
	v_mfma_f32_16x16x32_bf16 v[130:133], v[134:137], v[216:219], v[130:133]
	v_mfma_f32_16x16x32_bf16 v[126:129], v[154:157], v[216:219], v[126:129]
	v_mfma_f32_16x16x32_bf16 v[122:125], v[134:137], v[224:227], v[122:125]
	v_mfma_f32_16x16x32_bf16 v[118:121], v[154:157], v[224:227], v[118:121]
	v_mfma_f32_16x16x32_bf16 v[114:117], v[134:137], v[232:235], v[114:117]
	v_mfma_f32_16x16x32_bf16 v[110:113], v[154:157], v[232:235], v[110:113]
	v_mfma_f32_16x16x32_bf16 v[106:109], v[134:137], v[240:243], v[106:109]
	v_mfma_f32_16x16x32_bf16 v[102:105], v[154:157], v[240:243], v[102:105]
	v_mfma_f32_16x16x32_bf16 v[130:133], v[138:141], v[220:223], v[130:133]
	v_mfma_f32_16x16x32_bf16 v[126:129], v[158:161], v[220:223], v[126:129]
	v_mfma_f32_16x16x32_bf16 v[122:125], v[138:141], v[228:231], v[122:125]
	v_mfma_f32_16x16x32_bf16 v[118:121], v[158:161], v[228:231], v[118:121]
	v_mfma_f32_16x16x32_bf16 v[114:117], v[138:141], v[236:239], v[114:117]
	v_mfma_f32_16x16x32_bf16 v[110:113], v[158:161], v[236:239], v[110:113]
	v_mfma_f32_16x16x32_bf16 v[106:109], v[138:141], v[244:247], v[106:109]
	v_mfma_f32_16x16x32_bf16 v[102:105], v[158:161], v[244:247], v[102:105]
	v_mfma_f32_16x16x32_bf16 v[98:101], v[178:181], v[216:219], v[98:101]
	v_mfma_f32_16x16x32_bf16 v[94:97], v[208:211], v[216:219], v[94:97]
	v_mfma_f32_16x16x32_bf16 v[90:93], v[178:181], v[224:227], v[90:93]
	v_mfma_f32_16x16x32_bf16 v[86:89], v[208:211], v[224:227], v[86:89]
	v_mfma_f32_16x16x32_bf16 v[82:85], v[178:181], v[232:235], v[82:85]
	v_mfma_f32_16x16x32_bf16 v[78:81], v[208:211], v[232:235], v[78:81]
	v_mfma_f32_16x16x32_bf16 v[74:77], v[178:181], v[240:243], v[74:77]
	v_mfma_f32_16x16x32_bf16 v[70:73], v[208:211], v[240:243], v[70:73]
	v_mfma_f32_16x16x32_bf16 v[98:101], v[204:207], v[220:223], v[98:101]
	v_mfma_f32_16x16x32_bf16 v[94:97], v[212:215], v[220:223], v[94:97]
	v_mfma_f32_16x16x32_bf16 v[90:93], v[204:207], v[228:231], v[90:93]
	v_mfma_f32_16x16x32_bf16 v[86:89], v[212:215], v[228:231], v[86:89]
	v_mfma_f32_16x16x32_bf16 v[82:85], v[204:207], v[236:239], v[82:85]
	v_mfma_f32_16x16x32_bf16 v[78:81], v[212:215], v[236:239], v[78:81]
	v_mfma_f32_16x16x32_bf16 v[74:77], v[204:207], v[244:247], v[74:77]
	v_mfma_f32_16x16x32_bf16 v[70:73], v[212:215], v[244:247], v[70:73]
	s_setprio 3
	s_barrier
	s_add_i32 s29, s31, s54
	s_mov_b32 m0, s29
	ds_read_b128 v[216:219], v177 offset:16384
	ds_read_b128 v[220:223], v177 offset:17408
	ds_read_b128 v[224:227], v177 offset:18432
	ds_read_b128 v[228:231], v177 offset:19456
	ds_read_b128 v[232:235], v177 offset:20480
	ds_read_b128 v[236:239], v177 offset:21504
	ds_read_b128 v[240:243], v177 offset:22528
	ds_read_b128 v[244:247], v177 offset:23552
	global_load_lds_dwordx4 v144, s[42:43]
	s_add_i32 m0, s29, 0x2000
	s_add_u32 s64, s42, 0x40000
	s_addc_u32 s65, s43, 0
	s_add_i32 s27, s27, s54
	global_load_lds_dwordx4 v148, s[42:43]
	s_mov_b32 m0, s27
	s_nop 0
	global_load_lds_dwordx4 v144, s[64:65]
	s_add_i32 m0, s27, 0x2000
	s_nop 0
	global_load_lds_dwordx4 v148, s[64:65]
	s_mov_b32 m0, s55
	s_nop 0
	global_load_lds_dwordx4 v142, s[44:45]
	s_mov_b32 m0, s56
	s_nop 0
	global_load_lds_dwordx4 v146, s[44:45]
	s_nop 0
	s_waitcnt vmcnt(8) lgkmcnt(0)
	s_barrier
	s_setprio 0
	s_waitcnt lgkmcnt(0)
	v_mfma_f32_16x16x32_bf16 v[66:69], v[134:137], v[216:219], v[66:69]
	v_mfma_f32_16x16x32_bf16 v[62:65], v[154:157], v[216:219], v[62:65]
	v_mfma_f32_16x16x32_bf16 v[58:61], v[134:137], v[224:227], v[58:61]
	v_mfma_f32_16x16x32_bf16 v[54:57], v[154:157], v[224:227], v[54:57]
	v_mfma_f32_16x16x32_bf16 v[50:53], v[134:137], v[232:235], v[50:53]
	v_mfma_f32_16x16x32_bf16 v[46:49], v[154:157], v[232:235], v[46:49]
	v_mfma_f32_16x16x32_bf16 v[42:45], v[134:137], v[240:243], v[42:45]
	v_mfma_f32_16x16x32_bf16 v[38:41], v[154:157], v[240:243], v[38:41]
	v_mfma_f32_16x16x32_bf16 v[66:69], v[138:141], v[220:223], v[66:69]
	v_mfma_f32_16x16x32_bf16 v[62:65], v[158:161], v[220:223], v[62:65]
	v_mfma_f32_16x16x32_bf16 v[58:61], v[138:141], v[228:231], v[58:61]
	v_mfma_f32_16x16x32_bf16 v[54:57], v[158:161], v[228:231], v[54:57]
	v_mfma_f32_16x16x32_bf16 v[50:53], v[138:141], v[236:239], v[50:53]
	v_mfma_f32_16x16x32_bf16 v[46:49], v[158:161], v[236:239], v[46:49]
	v_mfma_f32_16x16x32_bf16 v[42:45], v[138:141], v[244:247], v[42:45]
	v_mfma_f32_16x16x32_bf16 v[38:41], v[158:161], v[244:247], v[38:41]
	v_mfma_f32_16x16x32_bf16 v[34:37], v[178:181], v[216:219], v[34:37]
	v_mfma_f32_16x16x32_bf16 v[30:33], v[208:211], v[216:219], v[30:33]
	v_mfma_f32_16x16x32_bf16 v[26:29], v[178:181], v[224:227], v[26:29]
	v_mfma_f32_16x16x32_bf16 v[22:25], v[208:211], v[224:227], v[22:25]
	v_mfma_f32_16x16x32_bf16 v[18:21], v[178:181], v[232:235], v[18:21]
	v_mfma_f32_16x16x32_bf16 v[14:17], v[208:211], v[232:235], v[14:17]
	v_mfma_f32_16x16x32_bf16 v[10:13], v[178:181], v[240:243], v[10:13]
	v_mfma_f32_16x16x32_bf16 v[4:7], v[208:211], v[240:243], v[6:9]
	v_mfma_f32_16x16x32_bf16 v[34:37], v[204:207], v[220:223], v[34:37]
	v_mfma_f32_16x16x32_bf16 v[30:33], v[212:215], v[220:223], v[30:33]
	v_mfma_f32_16x16x32_bf16 v[26:29], v[204:207], v[228:231], v[26:29]
	v_mfma_f32_16x16x32_bf16 v[22:25], v[212:215], v[228:231], v[22:25]
	v_mfma_f32_16x16x32_bf16 v[18:21], v[204:207], v[236:239], v[18:21]
	v_mfma_f32_16x16x32_bf16 v[14:17], v[212:215], v[236:239], v[14:17]
	v_mfma_f32_16x16x32_bf16 v[10:13], v[204:207], v[244:247], v[10:13]
	v_mfma_f32_16x16x32_bf16 v[4:7], v[212:215], v[244:247], v[4:7]
	s_setprio 3
	s_barrier
; #define PG8_STAGE(bufoff, gbase, voff) do { _Pragma("unroll") for (int _i = 0; _i < 2; ++_i) \
;         __builtin_amdgcn_global_load_lds((const unsigned*)((const char*)(gbase) + (voff)[_i]), (PG8_LAS unsigned*)(lds + (bufoff) + ldsw + _i * 8192), 16, 0, 0); } while (0)
; #define PG8_LDA(dst, b, h) do { _Pragma("unroll") for (int m = 0; m < 4; ++m) _Pragma("unroll") for (int k = 0; k < 2; ++k) dst[m][k] = *(const PG8_LAS bf16x8*)(lds + PG8_SA(b, h) + aoff + m * 2048 + k * 1024); } while (0)
; #define PG8_LDB(dst, b, h) do { _Pragma("unroll") for (int n = 0; n < 2; ++n) _Pragma("unroll") for (int k = 0; k < 2; ++k) dst[n][k] = *(const PG8_LAS bf16x8*)(lds + PG8_SB(b, h) + boff + n * 2048 + k * 1024); } while (0)
; #define PG8_MMA(ai, bj, At, Bt) do { __builtin_amdgcn_s_setprio(1); _Pragma("unroll") for (int m = 0; m < 4; ++m) _Pragma("unroll") for (int n = 0; n < 2; ++n) _Pragma("unroll") for (int k = 0; k < 2; ++k) \
;         acc[ai][bj][m][n] = __builtin_amdgcn_mfma_f32_16x16x32_bf16(Bt[n][k], At[m][k], acc[ai][bj][m][n], 0, 0, 0); __builtin_amdgcn_s_setprio(0); } while (0)
; #define PG8_WAIT_V(n) asm volatile("s_waitcnt vmcnt(" #n ")" ::: "memory")
; #define PG8_WAIT_L(n) asm volatile("s_waitcnt lgkmcnt(" #n ")" ::: "memory")
; #define PG8_BAR __builtin_amdgcn_s_barrier()
; #define PG8_SCHED __builtin_amdgcn_sched_barrier(0)
; template <class Epi, class Sched, bool ALIGN_EPI = false, bool SP2 = false>
; __device__ __forceinline__ void gemm_phase(PG8_LAS unsigned char* lds, const Gemm g, const Sched& S, const Epi& E) {
;     ...
;             PG8_LDB(B0, 1, 0); PG8_LDB(B1, 1, 1); PG8_SCHED; PG8_LDA(At, 1, 0); PG8_STAGE(PG8_SA(0, 1), a2 + hstep, voffA);
;             PG8_WAIT_V(8); PG8_WAIT_L(0); PG8_BAR; PG8_MMA(0, 0, At, B0); PG8_MMA(0, 1, At, B1); PG8_BAR; PG8_SCHED;
;             PG8_LDA(At, 1, 1); PG8_STAGE(PG8_SB(1, 0), b3, voffB); PG8_STAGE(PG8_SB(1, 1), b3 + hstep, voffB); PG8_STAGE(PG8_SA(1, 0), a3, voffA);
;             PG8_WAIT_V(8); PG8_WAIT_L(0); PG8_BAR; PG8_MMA(1, 0, At, B0); PG8_MMA(1, 1, At, B1); PG8_BAR; PG8_SCHED;
	s_add_i32 s27, 0, 0x18000
	v_add_u32_e32 v2, s27, v173
	s_add_i32 s29, 0, 0x1c000
	ds_read_b128 v[134:137], v2
	ds_read_b128 v[138:141], v2 offset:1024
	ds_read_b128 v[154:157], v2 offset:2048
	ds_read_b128 v[158:161], v2 offset:3072
	v_add_u32_e32 v2, s29, v173
	ds_read_b128 v[178:181], v2
	ds_read_b128 v[204:207], v2 offset:1024
	ds_read_b128 v[208:211], v2 offset:2048
	ds_read_b128 v[212:215], v2 offset:3072
	s_add_u32 s100, s44, 0x80
	s_addc_u32 s101, s45, 0
	s_add_u32 s44, s44, 0x40000
	s_addc_u32 s45, s45, 0
	s_mov_b32 m0, s57
	ds_read_b128 v[216:219], v177 offset:32768
	ds_read_b128 v[220:223], v177 offset:33792
	ds_read_b128 v[224:227], v177 offset:34816
	ds_read_b128 v[228:231], v177 offset:35840
	ds_read_b128 v[232:235], v177 offset:36864
	ds_read_b128 v[236:239], v177 offset:37888
	ds_read_b128 v[240:243], v177 offset:38912
	ds_read_b128 v[244:247], v177 offset:39936
	global_load_lds_dwordx4 v142, s[44:45]
	s_mov_b32 m0, s58
	s_nop 0
	global_load_lds_dwordx4 v146, s[44:45]
	s_nop 0
	s_waitcnt vmcnt(8) lgkmcnt(0)
	s_barrier
	s_setprio 0
	s_waitcnt lgkmcnt(0)
	v_mfma_f32_16x16x32_bf16 v[130:133], v[134:137], v[216:219], v[130:133]
	v_mfma_f32_16x16x32_bf16 v[126:129], v[154:157], v[216:219], v[126:129]
	v_mfma_f32_16x16x32_bf16 v[122:125], v[134:137], v[224:227], v[122:125]
	v_mfma_f32_16x16x32_bf16 v[118:121], v[154:157], v[224:227], v[118:121]
	v_mfma_f32_16x16x32_bf16 v[114:117], v[134:137], v[232:235], v[114:117]
	v_mfma_f32_16x16x32_bf16 v[110:113], v[154:157], v[232:235], v[110:113]
	v_mfma_f32_16x16x32_bf16 v[106:109], v[134:137], v[240:243], v[106:109]
	v_mfma_f32_16x16x32_bf16 v[102:105], v[154:157], v[240:243], v[102:105]
	v_mfma_f32_16x16x32_bf16 v[130:133], v[138:141], v[220:223], v[130:133]
	v_mfma_f32_16x16x32_bf16 v[126:129], v[158:161], v[220:223], v[126:129]
	v_mfma_f32_16x16x32_bf16 v[122:125], v[138:141], v[228:231], v[122:125]
	v_mfma_f32_16x16x32_bf16 v[118:121], v[158:161], v[228:231], v[118:121]
	v_mfma_f32_16x16x32_bf16 v[114:117], v[138:141], v[236:239], v[114:117]
	v_mfma_f32_16x16x32_bf16 v[110:113], v[158:161], v[236:239], v[110:113]
	v_mfma_f32_16x16x32_bf16 v[106:109], v[138:141], v[244:247], v[106:109]
	v_mfma_f32_16x16x32_bf16 v[102:105], v[158:161], v[244:247], v[102:105]
	v_mfma_f32_16x16x32_bf16 v[98:101], v[178:181], v[216:219], v[98:101]
	v_mfma_f32_16x16x32_bf16 v[94:97], v[208:211], v[216:219], v[94:97]
	v_mfma_f32_16x16x32_bf16 v[90:93], v[178:181], v[224:227], v[90:93]
	v_mfma_f32_16x16x32_bf16 v[86:89], v[208:211], v[224:227], v[86:89]
	v_mfma_f32_16x16x32_bf16 v[82:85], v[178:181], v[232:235], v[82:85]
	v_mfma_f32_16x16x32_bf16 v[78:81], v[208:211], v[232:235], v[78:81]
	v_mfma_f32_16x16x32_bf16 v[74:77], v[178:181], v[240:243], v[74:77]
	v_mfma_f32_16x16x32_bf16 v[70:73], v[208:211], v[240:243], v[70:73]
	v_mfma_f32_16x16x32_bf16 v[98:101], v[204:207], v[220:223], v[98:101]
	v_mfma_f32_16x16x32_bf16 v[94:97], v[212:215], v[220:223], v[94:97]
	v_mfma_f32_16x16x32_bf16 v[90:93], v[204:207], v[228:231], v[90:93]
	v_mfma_f32_16x16x32_bf16 v[86:89], v[212:215], v[228:231], v[86:89]
	v_mfma_f32_16x16x32_bf16 v[82:85], v[204:207], v[236:239], v[82:85]
	v_mfma_f32_16x16x32_bf16 v[78:81], v[212:215], v[236:239], v[78:81]
	v_mfma_f32_16x16x32_bf16 v[74:77], v[204:207], v[244:247], v[74:77]
	v_mfma_f32_16x16x32_bf16 v[70:73], v[212:215], v[244:247], v[70:73]
	s_setprio 3
	s_barrier
	s_add_i32 s27, s27, s54
	s_add_i32 m0, s27, 0xffffff80
	ds_read_b128 v[216:219], v177 offset:49152
	ds_read_b128 v[220:223], v177 offset:50176
	ds_read_b128 v[224:227], v177 offset:51200
	ds_read_b128 v[228:231], v177 offset:52224
	ds_read_b128 v[232:235], v177 offset:53248
	ds_read_b128 v[236:239], v177 offset:54272
	ds_read_b128 v[240:243], v177 offset:55296
	ds_read_b128 v[244:247], v177 offset:56320
	global_load_lds_dwordx4 v144, s[42:43] offset:128
	s_add_i32 m0, s27, 0x1f80
	s_add_i32 s27, s29, s54
	global_load_lds_dwordx4 v148, s[42:43] offset:128
	s_add_u32 s42, s42, 0x40080
	s_addc_u32 s43, s43, 0
	s_mov_b32 m0, s27
	s_nop 0
	global_load_lds_dwordx4 v144, s[42:43]
	s_add_i32 m0, s27, 0x2000
	s_nop 0
	global_load_lds_dwordx4 v148, s[42:43]
	s_mov_b32 m0, s61
	s_nop 0
	global_load_lds_dwordx4 v142, s[100:101]
	s_mov_b32 m0, s62
	s_nop 0
	global_load_lds_dwordx4 v146, s[100:101]
	s_waitcnt vmcnt(8) lgkmcnt(0)
	s_barrier
	s_setprio 0
	s_waitcnt lgkmcnt(0)
	v_mfma_f32_16x16x32_bf16 v[66:69], v[134:137], v[216:219], v[66:69]
	v_mfma_f32_16x16x32_bf16 v[62:65], v[154:157], v[216:219], v[62:65]
	v_mfma_f32_16x16x32_bf16 v[58:61], v[134:137], v[224:227], v[58:61]
	v_mfma_f32_16x16x32_bf16 v[54:57], v[154:157], v[224:227], v[54:57]
	v_mfma_f32_16x16x32_bf16 v[50:53], v[134:137], v[232:235], v[50:53]
	v_mfma_f32_16x16x32_bf16 v[46:49], v[154:157], v[232:235], v[46:49]
	v_mfma_f32_16x16x32_bf16 v[42:45], v[134:137], v[240:243], v[42:45]
	v_mfma_f32_16x16x32_bf16 v[38:41], v[154:157], v[240:243], v[38:41]
	v_mfma_f32_16x16x32_bf16 v[66:69], v[138:141], v[220:223], v[66:69]
	v_mfma_f32_16x16x32_bf16 v[62:65], v[158:161], v[220:223], v[62:65]
	v_mfma_f32_16x16x32_bf16 v[58:61], v[138:141], v[228:231], v[58:61]
	v_mfma_f32_16x16x32_bf16 v[54:57], v[158:161], v[228:231], v[54:57]
	v_mfma_f32_16x16x32_bf16 v[50:53], v[138:141], v[236:239], v[50:53]
	v_mfma_f32_16x16x32_bf16 v[46:49], v[158:161], v[236:239], v[46:49]
	v_mfma_f32_16x16x32_bf16 v[42:45], v[138:141], v[244:247], v[42:45]
	v_mfma_f32_16x16x32_bf16 v[38:41], v[158:161], v[244:247], v[38:41]
	v_mfma_f32_16x16x32_bf16 v[34:37], v[178:181], v[216:219], v[34:37]
	v_mfma_f32_16x16x32_bf16 v[30:33], v[208:211], v[216:219], v[30:33]
	v_mfma_f32_16x16x32_bf16 v[26:29], v[178:181], v[224:227], v[26:29]
	v_mfma_f32_16x16x32_bf16 v[22:25], v[208:211], v[224:227], v[22:25]
	v_mfma_f32_16x16x32_bf16 v[18:21], v[178:181], v[232:235], v[18:21]
	v_mfma_f32_16x16x32_bf16 v[14:17], v[208:211], v[232:235], v[14:17]
	v_mfma_f32_16x16x32_bf16 v[8:11], v[178:181], v[240:243], v[10:13]
	v_mfma_f32_16x16x32_bf16 v[4:7], v[208:211], v[240:243], v[4:7]
	v_mfma_f32_16x16x32_bf16 v[34:37], v[204:207], v[220:223], v[34:37]
	v_mfma_f32_16x16x32_bf16 v[30:33], v[212:215], v[220:223], v[30:33]
	v_mfma_f32_16x16x32_bf16 v[26:29], v[204:207], v[228:231], v[26:29]
	v_mfma_f32_16x16x32_bf16 v[22:25], v[212:215], v[228:231], v[22:25]
	v_mfma_f32_16x16x32_bf16 v[18:21], v[204:207], v[236:239], v[18:21]
	v_mfma_f32_16x16x32_bf16 v[14:17], v[212:215], v[236:239], v[14:17]
	v_mfma_f32_16x16x32_bf16 v[10:13], v[204:207], v[244:247], v[8:11]
	v_mfma_f32_16x16x32_bf16 v[6:9], v[212:215], v[244:247], v[4:7]
	s_setprio 3
	s_barrier
	s_add_i32 s26, s26, 2
	s_add_u32 s40, s40, 0x100
	s_addc_u32 s41, s41, 0
	s_add_u32 s11, s11, 0x100
	s_addc_u32 s13, s13, 0
	s_cmp_gt_u32 s26, 13
	s_cbranch_scc0 .LBB0_2096
	s_and_b64 vcc, exec, s[8:9]
	s_cbranch_vccz .LBB0_2099
	s_barrier

; #define PG8_STAGE(bufoff, gbase, voff) do { _Pragma("unroll") for (int _i = 0; _i < 2; ++_i) \
;         __builtin_amdgcn_global_load_lds((const unsigned*)((const char*)(gbase) + (voff)[_i]), (PG8_LAS unsigned*)(lds + (bufoff) + ldsw + _i * 8192), 16, 0, 0); } while (0)
; #define PG8_LDA(dst, b, h) do { _Pragma("unroll") for (int m = 0; m < 4; ++m) _Pragma("unroll") for (int k = 0; k < 2; ++k) dst[m][k] = *(const PG8_LAS bf16x8*)(lds + PG8_SA(b, h) + aoff + m * 2048 + k * 1024); } while (0)
; #define PG8_LDB(dst, b, h) do { _Pragma("unroll") for (int n = 0; n < 2; ++n) _Pragma("unroll") for (int k = 0; k < 2; ++k) dst[n][k] = *(const PG8_LAS bf16x8*)(lds + PG8_SB(b, h) + boff + n * 2048 + k * 1024); } while (0)
; #define PG8_MMA(ai, bj, At, Bt) do { __builtin_amdgcn_s_setprio(1); _Pragma("unroll") for (int m = 0; m < 4; ++m) _Pragma("unroll") for (int n = 0; n < 2; ++n) _Pragma("unroll") for (int k = 0; k < 2; ++k) \
;         acc[ai][bj][m][n] = __builtin_amdgcn_mfma_f32_16x16x32_bf16(Bt[n][k], At[m][k], acc[ai][bj][m][n], 0, 0, 0); __builtin_amdgcn_s_setprio(0); } while (0)
; #define PG8_WAIT_V(n) asm volatile("s_waitcnt vmcnt(" #n ")" ::: "memory")
; #define PG8_WAIT_L(n) asm volatile("s_waitcnt lgkmcnt(" #n ")" ::: "memory")
; template <class Epi, class Sched, bool ALIGN_EPI = false, bool SP2 = false>
; __device__ __forceinline__ void gemm_phase(PG8_LAS unsigned char* lds, const Gemm g, const Sched& S, const Epi& E) {
;     ...
;             const bool last = (t == nt - 2);
;             const char* a1 = cA + (size_t)(t + 1) * kstep;
;             const char* a2 = last ? nA : cA + (size_t)(t + 2) * kstep; const char* b2 = last ? nB : cB + (size_t)(t + 2) * kstep;
;             const char* a3 = a2 + kstep; const char* b3 = b2 + kstep;
;             if (last && has_next) S.a_ready(nxt);
;             if constexpr (SP2) {
;             PG8_LDB(B0, 0, 0); PG8_LDB(B1, 0, 1); PG8_SCHED; PG8_LDA(At, 0, 0); PG8_STAGE(PG8_SA(1, 1), a1 + hstep, voffA);
;             PG8_WAIT_V(8); PG8_WAIT_L(0); PG8_BAR; PG8_MMA(0, 0, At, B0); PG8_MMA(0, 1, At, B1); PG8_BAR; PG8_SCHED;
;             PG8_LDA(At, 0, 1); PG8_STAGE(PG8_SB(0, 0), b2, voffB); PG8_STAGE(PG8_SB(0, 1), b2 + hstep, voffB); PG8_STAGE(PG8_SA(0, 0), a2, voffA);
;             PG8_WAIT_V(8); PG8_WAIT_L(0); PG8_BAR; PG8_MMA(1, 0, At, B0); PG8_MMA(1, 1, At, B1); PG8_BAR; PG8_SCHED;
.LBB0_2185:
	s_add_u32 s42, s40, 0x100
	s_addc_u32 s43, s41, 0
	s_add_i32 s37, 0, 0x10000
	s_cmp_eq_u32 s31, 28
	s_cselect_b32 s47, s5, s43
	s_cselect_b32 s46, s4, s42
	v_add_u32_e32 v135, s37, v173
	s_cselect_b32 s45, s35, s29
	s_cselect_b32 s44, s34, s2
	s_add_i32 s39, 0, 0x14000
	ds_read_b128 v[142:145], v135
	ds_read_b128 v[146:149], v135 offset:1024
	ds_read_b128 v[150:153], v135 offset:2048
	ds_read_b128 v[154:157], v135 offset:3072
	v_add_u32_e32 v135, s39, v173
	ds_read_b128 v[158:161], v135
	ds_read_b128 v[174:177], v135 offset:1024
	ds_read_b128 v[180:183], v135 offset:2048
	ds_read_b128 v[204:207], v135 offset:3072
	v_lshl_add_u64 v[162:163], s[40:41], 0, v[138:139]
	s_add_i32 m0, s55, 0xc000
	ds_read_b128 v[208:211], v179
	ds_read_b128 v[212:215], v179 offset:1024
	ds_read_b128 v[216:219], v179 offset:2048
	ds_read_b128 v[220:223], v179 offset:3072
	ds_read_b128 v[224:227], v179 offset:4096
	ds_read_b128 v[228:231], v179 offset:5120
	ds_read_b128 v[232:235], v179 offset:6144
	ds_read_b128 v[236:239], v179 offset:7168
	global_load_lds_dwordx4 v[162:163], off
	v_lshl_add_u64 v[162:163], s[40:41], 0, v[140:141]
	s_add_i32 m0, s55, 0xe000
	s_nop 0
	global_load_lds_dwordx4 v[162:163], off
	s_nop 0
	s_waitcnt vmcnt(8) lgkmcnt(0)
	s_barrier
	s_setprio 0
	s_waitcnt lgkmcnt(0)
	v_mfma_f32_16x16x32_bf16 v[128:131], v[142:145], v[208:211], v[128:131]
	v_mfma_f32_16x16x32_bf16 v[124:127], v[150:153], v[208:211], v[124:127]
	v_mfma_f32_16x16x32_bf16 v[112:115], v[142:145], v[216:219], v[112:115]
	v_mfma_f32_16x16x32_bf16 v[108:111], v[150:153], v[216:219], v[108:111]
	v_mfma_f32_16x16x32_bf16 v[96:99], v[142:145], v[224:227], v[96:99]
	v_mfma_f32_16x16x32_bf16 v[92:95], v[150:153], v[224:227], v[92:95]
	v_mfma_f32_16x16x32_bf16 v[80:83], v[142:145], v[232:235], v[80:83]
	v_mfma_f32_16x16x32_bf16 v[76:79], v[150:153], v[232:235], v[76:79]
	v_mfma_f32_16x16x32_bf16 v[128:131], v[146:149], v[212:215], v[128:131]
	v_mfma_f32_16x16x32_bf16 v[124:127], v[154:157], v[212:215], v[124:127]
	v_mfma_f32_16x16x32_bf16 v[112:115], v[146:149], v[220:223], v[112:115]
	v_mfma_f32_16x16x32_bf16 v[108:111], v[154:157], v[220:223], v[108:111]
	v_mfma_f32_16x16x32_bf16 v[96:99], v[146:149], v[228:231], v[96:99]
	v_mfma_f32_16x16x32_bf16 v[92:95], v[154:157], v[228:231], v[92:95]
	v_mfma_f32_16x16x32_bf16 v[80:83], v[146:149], v[236:239], v[80:83]
	v_mfma_f32_16x16x32_bf16 v[76:79], v[154:157], v[236:239], v[76:79]
	v_mfma_f32_16x16x32_bf16 v[120:123], v[158:161], v[208:211], v[120:123]
	v_mfma_f32_16x16x32_bf16 v[116:119], v[180:183], v[208:211], v[116:119]
	v_mfma_f32_16x16x32_bf16 v[104:107], v[158:161], v[216:219], v[104:107]
	v_mfma_f32_16x16x32_bf16 v[100:103], v[180:183], v[216:219], v[100:103]
	v_mfma_f32_16x16x32_bf16 v[88:91], v[158:161], v[224:227], v[88:91]
	v_mfma_f32_16x16x32_bf16 v[84:87], v[180:183], v[224:227], v[84:87]
	v_mfma_f32_16x16x32_bf16 v[72:75], v[158:161], v[232:235], v[72:75]
	v_mfma_f32_16x16x32_bf16 v[68:71], v[180:183], v[232:235], v[68:71]
	v_mfma_f32_16x16x32_bf16 v[120:123], v[174:177], v[212:215], v[120:123]
	v_mfma_f32_16x16x32_bf16 v[116:119], v[204:207], v[212:215], v[116:119]
	v_mfma_f32_16x16x32_bf16 v[104:107], v[174:177], v[220:223], v[104:107]
	v_mfma_f32_16x16x32_bf16 v[100:103], v[204:207], v[220:223], v[100:103]
	v_mfma_f32_16x16x32_bf16 v[88:91], v[174:177], v[228:231], v[88:91]
	v_mfma_f32_16x16x32_bf16 v[84:87], v[204:207], v[228:231], v[84:87]
	v_mfma_f32_16x16x32_bf16 v[72:75], v[174:177], v[236:239], v[72:75]
	v_mfma_f32_16x16x32_bf16 v[68:71], v[204:207], v[236:239], v[68:71]
	s_setprio 3
	s_barrier
	s_add_i32 s37, s37, s54
	s_mov_b32 m0, s37
	ds_read_b128 v[208:211], v179 offset:16384
	ds_read_b128 v[212:215], v179 offset:17408
	ds_read_b128 v[216:219], v179 offset:18432
	ds_read_b128 v[220:223], v179 offset:19456
	ds_read_b128 v[224:227], v179 offset:20480
	ds_read_b128 v[228:231], v179 offset:21504
	ds_read_b128 v[232:235], v179 offset:22528
	ds_read_b128 v[236:239], v179 offset:23552
	global_load_lds_dwordx4 v2, s[44:45]
	s_add_i32 m0, s37, 0x2000
	s_add_u32 s40, s44, 0x80000
	s_addc_u32 s41, s45, 0
	s_add_i32 s37, s39, s54
	global_load_lds_dwordx4 v132, s[44:45]
	s_mov_b32 m0, s37
	s_nop 0
	global_load_lds_dwordx4 v2, s[40:41]
	s_add_i32 m0, s37, 0x2000
	s_nop 0
	global_load_lds_dwordx4 v132, s[40:41]
	s_mov_b32 m0, s55
	s_nop 0
	global_load_lds_dwordx4 v2, s[46:47]
	s_mov_b32 m0, s56
	s_nop 0
	global_load_lds_dwordx4 v132, s[46:47]
	s_nop 0
	s_waitcnt vmcnt(8) lgkmcnt(0)
	s_barrier
	s_setprio 0
	s_waitcnt lgkmcnt(0)
	v_mfma_f32_16x16x32_bf16 v[64:67], v[142:145], v[208:211], v[64:67]
	v_mfma_f32_16x16x32_bf16 v[60:63], v[150:153], v[208:211], v[60:63]
	v_mfma_f32_16x16x32_bf16 v[48:51], v[142:145], v[216:219], v[48:51]
	v_mfma_f32_16x16x32_bf16 v[44:47], v[150:153], v[216:219], v[44:47]
	v_mfma_f32_16x16x32_bf16 v[32:35], v[142:145], v[224:227], v[32:35]
	v_mfma_f32_16x16x32_bf16 v[28:31], v[150:153], v[224:227], v[28:31]
	v_mfma_f32_16x16x32_bf16 v[16:19], v[142:145], v[232:235], v[16:19]
	v_mfma_f32_16x16x32_bf16 v[12:15], v[150:153], v[232:235], v[12:15]
	v_mfma_f32_16x16x32_bf16 v[64:67], v[146:149], v[212:215], v[64:67]
	v_mfma_f32_16x16x32_bf16 v[60:63], v[154:157], v[212:215], v[60:63]
	v_mfma_f32_16x16x32_bf16 v[48:51], v[146:149], v[220:223], v[48:51]
	v_mfma_f32_16x16x32_bf16 v[44:47], v[154:157], v[220:223], v[44:47]
	v_mfma_f32_16x16x32_bf16 v[32:35], v[146:149], v[228:231], v[32:35]
	v_mfma_f32_16x16x32_bf16 v[28:31], v[154:157], v[228:231], v[28:31]
	v_mfma_f32_16x16x32_bf16 v[16:19], v[146:149], v[236:239], v[16:19]
	v_mfma_f32_16x16x32_bf16 v[12:15], v[154:157], v[236:239], v[12:15]
	v_mfma_f32_16x16x32_bf16 v[56:59], v[158:161], v[208:211], v[56:59]
	v_mfma_f32_16x16x32_bf16 v[52:55], v[180:183], v[208:211], v[52:55]
	v_mfma_f32_16x16x32_bf16 v[40:43], v[158:161], v[216:219], v[40:43]
	v_mfma_f32_16x16x32_bf16 v[36:39], v[180:183], v[216:219], v[36:39]
	v_mfma_f32_16x16x32_bf16 v[24:27], v[158:161], v[224:227], v[24:27]
	v_mfma_f32_16x16x32_bf16 v[20:23], v[180:183], v[224:227], v[20:23]
	v_mfma_f32_16x16x32_bf16 v[8:11], v[158:161], v[232:235], v[8:11]
	v_mfma_f32_16x16x32_bf16 v[4:7], v[180:183], v[232:235], v[4:7]
	v_mfma_f32_16x16x32_bf16 v[56:59], v[174:177], v[212:215], v[56:59]
	v_mfma_f32_16x16x32_bf16 v[52:55], v[204:207], v[212:215], v[52:55]
	v_mfma_f32_16x16x32_bf16 v[40:43], v[174:177], v[220:223], v[40:43]
	v_mfma_f32_16x16x32_bf16 v[36:39], v[204:207], v[220:223], v[36:39]
	v_mfma_f32_16x16x32_bf16 v[24:27], v[174:177], v[228:231], v[24:27]
	v_mfma_f32_16x16x32_bf16 v[20:23], v[204:207], v[228:231], v[20:23]
	v_mfma_f32_16x16x32_bf16 v[8:11], v[174:177], v[236:239], v[8:11]
	v_mfma_f32_16x16x32_bf16 v[4:7], v[204:207], v[236:239], v[4:7]
	s_setprio 3
	s_barrier
; #define PG8_STAGE(bufoff, gbase, voff) do { _Pragma("unroll") for (int _i = 0; _i < 2; ++_i) \
;         __builtin_amdgcn_global_load_lds((const unsigned*)((const char*)(gbase) + (voff)[_i]), (PG8_LAS unsigned*)(lds + (bufoff) + ldsw + _i * 8192), 16, 0, 0); } while (0)
; #define PG8_LDA(dst, b, h) do { _Pragma("unroll") for (int m = 0; m < 4; ++m) _Pragma("unroll") for (int k = 0; k < 2; ++k) dst[m][k] = *(const PG8_LAS bf16x8*)(lds + PG8_SA(b, h) + aoff + m * 2048 + k * 1024); } while (0)
; #define PG8_LDB(dst, b, h) do { _Pragma("unroll") for (int n = 0; n < 2; ++n) _Pragma("unroll") for (int k = 0; k < 2; ++k) dst[n][k] = *(const PG8_LAS bf16x8*)(lds + PG8_SB(b, h) + boff + n * 2048 + k * 1024); } while (0)
; #define PG8_MMA(ai, bj, At, Bt) do { __builtin_amdgcn_s_setprio(1); _Pragma("unroll") for (int m = 0; m < 4; ++m) _Pragma("unroll") for (int n = 0; n < 2; ++n) _Pragma("unroll") for (int k = 0; k < 2; ++k) \
;         acc[ai][bj][m][n] = __builtin_amdgcn_mfma_f32_16x16x32_bf16(Bt[n][k], At[m][k], acc[ai][bj][m][n], 0, 0, 0); __builtin_amdgcn_s_setprio(0); } while (0)
; #define PG8_WAIT_V(n) asm volatile("s_waitcnt vmcnt(" #n ")" ::: "memory")
; #define PG8_WAIT_L(n) asm volatile("s_waitcnt lgkmcnt(" #n ")" ::: "memory")
; #define PG8_BAR __builtin_amdgcn_s_barrier()
; #define PG8_SCHED __builtin_amdgcn_sched_barrier(0)
; template <class Epi, class Sched, bool ALIGN_EPI = false, bool SP2 = false>
; __device__ __forceinline__ void gemm_phase(PG8_LAS unsigned char* lds, const Gemm g, const Sched& S, const Epi& E) {
;     ...
;             PG8_LDB(B0, 1, 0); PG8_LDB(B1, 1, 1); PG8_SCHED; PG8_LDA(At, 1, 0); PG8_STAGE(PG8_SA(0, 1), a2 + hstep, voffA);
;             PG8_WAIT_V(8); PG8_WAIT_L(0); PG8_BAR; PG8_MMA(0, 0, At, B0); PG8_MMA(0, 1, At, B1); PG8_BAR; PG8_SCHED;
;             PG8_LDA(At, 1, 1); PG8_STAGE(PG8_SB(1, 0), b3, voffB); PG8_STAGE(PG8_SB(1, 1), b3 + hstep, voffB); PG8_STAGE(PG8_SA(1, 0), a3, voffA);
;             PG8_WAIT_V(8); PG8_WAIT_L(0); PG8_BAR; PG8_MMA(1, 0, At, B0); PG8_MMA(1, 1, At, B1); PG8_BAR; PG8_SCHED;
	s_add_i32 s37, 0, 0x18000
	v_add_u32_e32 v135, s37, v173
	s_add_i32 s39, 0, 0x1c000
	ds_read_b128 v[142:145], v135
	ds_read_b128 v[146:149], v135 offset:1024
	ds_read_b128 v[150:153], v135 offset:2048
	ds_read_b128 v[154:157], v135 offset:3072
	v_add_u32_e32 v135, s39, v173
	ds_read_b128 v[158:161], v135
	ds_read_b128 v[174:177], v135 offset:1024
	ds_read_b128 v[180:183], v135 offset:2048
	ds_read_b128 v[204:207], v135 offset:3072
	s_add_u32 s40, s46, 0x80000
	s_addc_u32 s41, s47, 0
	s_mov_b32 m0, s57
	ds_read_b128 v[208:211], v179 offset:32768
	ds_read_b128 v[212:215], v179 offset:33792
	ds_read_b128 v[216:219], v179 offset:34816
	ds_read_b128 v[220:223], v179 offset:35840
	ds_read_b128 v[224:227], v179 offset:36864
	ds_read_b128 v[228:231], v179 offset:37888
	ds_read_b128 v[232:235], v179 offset:38912
	ds_read_b128 v[236:239], v179 offset:39936
	global_load_lds_dwordx4 v2, s[40:41]
	s_mov_b32 m0, s58
	s_nop 0
	global_load_lds_dwordx4 v132, s[40:41]
	s_waitcnt vmcnt(8) lgkmcnt(0)
	s_barrier
	s_setprio 0
	s_waitcnt lgkmcnt(0)
	v_mfma_f32_16x16x32_bf16 v[128:131], v[142:145], v[208:211], v[128:131]
	v_mfma_f32_16x16x32_bf16 v[124:127], v[150:153], v[208:211], v[124:127]
	v_mfma_f32_16x16x32_bf16 v[112:115], v[142:145], v[216:219], v[112:115]
	v_mfma_f32_16x16x32_bf16 v[108:111], v[150:153], v[216:219], v[108:111]
	v_mfma_f32_16x16x32_bf16 v[96:99], v[142:145], v[224:227], v[96:99]
	v_mfma_f32_16x16x32_bf16 v[92:95], v[150:153], v[224:227], v[92:95]
	v_mfma_f32_16x16x32_bf16 v[80:83], v[142:145], v[232:235], v[80:83]
	v_mfma_f32_16x16x32_bf16 v[76:79], v[150:153], v[232:235], v[76:79]
	v_mfma_f32_16x16x32_bf16 v[128:131], v[146:149], v[212:215], v[128:131]
	v_mfma_f32_16x16x32_bf16 v[124:127], v[154:157], v[212:215], v[124:127]
	v_mfma_f32_16x16x32_bf16 v[112:115], v[146:149], v[220:223], v[112:115]
	v_mfma_f32_16x16x32_bf16 v[108:111], v[154:157], v[220:223], v[108:111]
	v_mfma_f32_16x16x32_bf16 v[96:99], v[146:149], v[228:231], v[96:99]
	v_mfma_f32_16x16x32_bf16 v[92:95], v[154:157], v[228:231], v[92:95]
	v_mfma_f32_16x16x32_bf16 v[80:83], v[146:149], v[236:239], v[80:83]
	v_mfma_f32_16x16x32_bf16 v[76:79], v[154:157], v[236:239], v[76:79]
	v_mfma_f32_16x16x32_bf16 v[120:123], v[158:161], v[208:211], v[120:123]
	v_mfma_f32_16x16x32_bf16 v[116:119], v[180:183], v[208:211], v[116:119]
	v_mfma_f32_16x16x32_bf16 v[104:107], v[158:161], v[216:219], v[104:107]
	v_mfma_f32_16x16x32_bf16 v[100:103], v[180:183], v[216:219], v[100:103]
	v_mfma_f32_16x16x32_bf16 v[88:91], v[158:161], v[224:227], v[88:91]
	v_mfma_f32_16x16x32_bf16 v[84:87], v[180:183], v[224:227], v[84:87]
	v_mfma_f32_16x16x32_bf16 v[72:75], v[158:161], v[232:235], v[72:75]
	v_mfma_f32_16x16x32_bf16 v[68:71], v[180:183], v[232:235], v[68:71]
	v_mfma_f32_16x16x32_bf16 v[120:123], v[174:177], v[212:215], v[120:123]
	v_mfma_f32_16x16x32_bf16 v[116:119], v[204:207], v[212:215], v[116:119]
	v_mfma_f32_16x16x32_bf16 v[104:107], v[174:177], v[220:223], v[104:107]
	v_mfma_f32_16x16x32_bf16 v[100:103], v[204:207], v[220:223], v[100:103]
	v_mfma_f32_16x16x32_bf16 v[88:91], v[174:177], v[228:231], v[88:91]
	v_mfma_f32_16x16x32_bf16 v[84:87], v[204:207], v[228:231], v[84:87]
	v_mfma_f32_16x16x32_bf16 v[72:75], v[174:177], v[236:239], v[72:75]
	v_mfma_f32_16x16x32_bf16 v[68:71], v[204:207], v[236:239], v[68:71]
	s_setprio 3
	s_barrier
	s_add_i32 s37, s37, s54
	s_add_i32 m0, s37, 0xffffff80
	ds_read_b128 v[208:211], v179 offset:49152
	ds_read_b128 v[212:215], v179 offset:50176
	ds_read_b128 v[216:219], v179 offset:51200
	ds_read_b128 v[220:223], v179 offset:52224
	ds_read_b128 v[224:227], v179 offset:53248
	ds_read_b128 v[228:231], v179 offset:54272
	ds_read_b128 v[232:235], v179 offset:55296
	ds_read_b128 v[236:239], v179 offset:56320
	global_load_lds_dwordx4 v2, s[44:45] offset:128
	s_add_i32 m0, s37, 0x1f80
	s_add_u32 s40, s44, 0x80080
	s_addc_u32 s41, s45, 0
	s_add_i32 s37, s39, s54
	global_load_lds_dwordx4 v132, s[44:45] offset:128
	s_mov_b32 m0, s37
	s_nop 0
	global_load_lds_dwordx4 v2, s[40:41]
	s_add_i32 m0, s37, 0x2000
	s_nop 0
	global_load_lds_dwordx4 v132, s[40:41]
	s_add_i32 m0, s60, 0xffffff80
	s_nop 0
	global_load_lds_dwordx4 v2, s[46:47] offset:128
	s_add_i32 m0, s61, 0xffffff80
	s_nop 0
	global_load_lds_dwordx4 v132, s[46:47] offset:128
	s_waitcnt vmcnt(8) lgkmcnt(0)
	s_barrier
	s_setprio 0
	s_waitcnt lgkmcnt(0)
	v_mfma_f32_16x16x32_bf16 v[64:67], v[142:145], v[208:211], v[64:67]
	v_mfma_f32_16x16x32_bf16 v[60:63], v[150:153], v[208:211], v[60:63]
	v_mfma_f32_16x16x32_bf16 v[48:51], v[142:145], v[216:219], v[48:51]
	v_mfma_f32_16x16x32_bf16 v[44:47], v[150:153], v[216:219], v[44:47]
	v_mfma_f32_16x16x32_bf16 v[32:35], v[142:145], v[224:227], v[32:35]
	v_mfma_f32_16x16x32_bf16 v[28:31], v[150:153], v[224:227], v[28:31]
	v_mfma_f32_16x16x32_bf16 v[16:19], v[142:145], v[232:235], v[16:19]
	v_mfma_f32_16x16x32_bf16 v[12:15], v[150:153], v[232:235], v[12:15]
	v_mfma_f32_16x16x32_bf16 v[64:67], v[146:149], v[212:215], v[64:67]
	v_mfma_f32_16x16x32_bf16 v[60:63], v[154:157], v[212:215], v[60:63]
	v_mfma_f32_16x16x32_bf16 v[48:51], v[146:149], v[220:223], v[48:51]
	v_mfma_f32_16x16x32_bf16 v[44:47], v[154:157], v[220:223], v[44:47]
	v_mfma_f32_16x16x32_bf16 v[32:35], v[146:149], v[228:231], v[32:35]
	v_mfma_f32_16x16x32_bf16 v[28:31], v[154:157], v[228:231], v[28:31]
	v_mfma_f32_16x16x32_bf16 v[16:19], v[146:149], v[236:239], v[16:19]
	v_mfma_f32_16x16x32_bf16 v[12:15], v[154:157], v[236:239], v[12:15]
	v_mfma_f32_16x16x32_bf16 v[56:59], v[158:161], v[208:211], v[56:59]
	v_mfma_f32_16x16x32_bf16 v[52:55], v[180:183], v[208:211], v[52:55]
	v_mfma_f32_16x16x32_bf16 v[40:43], v[158:161], v[216:219], v[40:43]
	v_mfma_f32_16x16x32_bf16 v[36:39], v[180:183], v[216:219], v[36:39]
	v_mfma_f32_16x16x32_bf16 v[24:27], v[158:161], v[224:227], v[24:27]
	v_mfma_f32_16x16x32_bf16 v[20:23], v[180:183], v[224:227], v[20:23]
	v_mfma_f32_16x16x32_bf16 v[8:11], v[158:161], v[232:235], v[8:11]
	v_mfma_f32_16x16x32_bf16 v[4:7], v[180:183], v[232:235], v[4:7]
	v_mfma_f32_16x16x32_bf16 v[56:59], v[174:177], v[212:215], v[56:59]
	v_mfma_f32_16x16x32_bf16 v[52:55], v[204:207], v[212:215], v[52:55]
	v_mfma_f32_16x16x32_bf16 v[40:43], v[174:177], v[220:223], v[40:43]
	v_mfma_f32_16x16x32_bf16 v[36:39], v[204:207], v[220:223], v[36:39]
	v_mfma_f32_16x16x32_bf16 v[24:27], v[174:177], v[228:231], v[24:27]
	v_mfma_f32_16x16x32_bf16 v[20:23], v[204:207], v[228:231], v[20:23]
	v_mfma_f32_16x16x32_bf16 v[8:11], v[174:177], v[236:239], v[8:11]
	v_mfma_f32_16x16x32_bf16 v[4:7], v[204:207], v[236:239], v[4:7]
	s_setprio 3
	s_barrier
	s_add_i32 s31, s31, 2
	s_add_u32 s2, s2, 0x100
	s_addc_u32 s29, s29, 0
	s_cmp_gt_u32 s31, 29
	s_mov_b64 s[40:41], s[42:43]
	s_cbranch_scc0 .LBB0_2185
	s_and_b64 vcc, exec, s[26:27]
	s_cbranch_vccz .LBB0_2188
	s_barrier
